# unit-loop header of P1/P4/P10: StaticOrder::next index math + next-unit base addresses moved off the unit-to-unit critical path into the second load segment of the peeled first K iteration; on top of
# baseline (speedup 1.0000x reference)
; template <class Epi, class Sched, bool ALIGN_EPI = false, bool SP2 = false>
; __device__ __forceinline__ void gemm_phase(PG8_LAS unsigned char* lds, const Gemm g, const Sched& S, const Epi& E, const int wid) {
;     ...
;         const bool has_next = S.next(ui + 1, nxt);
;         const char* nA = has_next ? (const char*)g.A + (size_t)nxt.pm * tstep : cA; const char* nB = has_next ? (const char*)g.Bt + (size_t)nxt.pn * tstep : cB;
;         for (int t = 0; t < nt; t += 2) {
;             const bool last = (t == nt - 2);
;             const char* a1 = cA + (size_t)(t + 1) * kstep;
;             const char* a2 = last ? nA : cA + (size_t)(t + 2) * kstep; const char* b2 = last ? nB : cB + (size_t)(t + 2) * kstep;
;             const char* a3 = a2 + kstep; const char* b3 = b2 + kstep;
.LBB0_266:
	s_add_u32 s22, s22, 0x40080
	s_addc_u32 s23, s23, 0
	s_add_u32 s46, s24, 0x100

; template <class Epi, class Sched, bool ALIGN_EPI = false, bool SP2 = false>
; __device__ __forceinline__ void gemm_phase(PG8_LAS unsigned char* lds, const Gemm g, const Sched& S, const Epi& E, const int wid) {
;     ...
;         for (int t = 0; t < nt; t += 2) {
;             const bool last = (t == nt - 2);
;             const char* a1 = cA + (size_t)(t + 1) * kstep;
;             const char* a2 = last ? nA : cA + (size_t)(t + 2) * kstep; const char* b2 = last ? nB : cB + (size_t)(t + 2) * kstep;
;             const char* a3 = a2 + kstep; const char* b3 = b2 + kstep;
	s_addc_u32 s47, s25, 0
	s_mov_b32 s48, -2


; #define PG8_STAGE(bufoff, gbase, voff) do { _Pragma("unroll") for (int _i = 0; _i < 2; ++_i) \
;         __builtin_amdgcn_global_load_lds((const unsigned*)((const char*)(gbase) + (voff)[_i]), (PG8_LAS unsigned*)(lds + (bufoff) + ldsw + _i * 8192), 16, 0, 0); } while (0)
; #define PG8_LDA(dst, b, h) do { _Pragma("unroll") for (int m = 0; m < 4; ++m) _Pragma("unroll") for (int k = 0; k < 2; ++k) dst[m][k] = *(const PG8_LAS bf16x8*)(lds + PG8_SA(b, h) + aoff + m * 2048 + k * 1024); } while (0)
; #define PG8_LDB(dst, b, h) do { _Pragma("unroll") for (int n = 0; n < 2; ++n) _Pragma("unroll") for (int k = 0; k < 2; ++k) dst[n][k] = *(const PG8_LAS bf16x8*)(lds + PG8_SB(b, h) + boff + n * 2048 + k * 1024); } while (0)
; #define PG8_MMA(ai, bj, At, Bt) do { __builtin_amdgcn_s_setprio(1); _Pragma("unroll") for (int m = 0; m < 4; ++m) _Pragma("unroll") for (int n = 0; n < 2; ++n) _Pragma("unroll") for (int k = 0; k < 2; ++k) \
;         acc[ai][bj][m][n] = __builtin_amdgcn_mfma_f32_16x16x32_bf16(Bt[n][k], At[m][k], acc[ai][bj][m][n], 0, 0, 0); __builtin_amdgcn_s_setprio(0); } while (0)
; #define PG8_BAR __builtin_amdgcn_s_barrier()
;     __host__ __device__ bool next(int i, Unit& u) const {
;         const long L = (long)i * G + c; if (L >= nwg) return false;
;         int wgid = (int)L; { const int q = nwg / NXCD, r = nwg % NXCD, xcd = wgid % NXCD, off = wgid / NXCD; wgid = (xcd < r ? xcd * (q + 1) : r * (q + 1) + (xcd - r) * q) + off; }
;         const int nig = WGM * nN, gid = wgid / nig, fm = gid * WGM, gsz = (nM - fm) < WGM ? (nM - fm) : WGM;
;         u.pm = fm + ((wgid % nig) % gsz); u.pn = (wgid % nig) / gsz; return true;
;     }
; template <class Epi, class Sched, bool ALIGN_EPI = false, bool SP2 = false>
; __device__ __forceinline__ void gemm_phase(PG8_LAS unsigned char* lds, const Gemm g, const Sched& S, const Epi& E, const int wid) {
;     ...
;             PG8_LDB(B0, 0, 0); PG8_LDB(B1, 0, 1); PG8_SCHED; PG8_LDA(At, 0, 0); PG8_STAGE(PG8_SA(1, 1), a1 + hstep, voffA);
;             PG8_WAIT_V(8); PG8_WAIT_L(0); PG8_BAR; PG8_MMA(0, 0, At, B0); PG8_MMA(0, 1, At, B1); PG8_BAR; PG8_SCHED;
;             PG8_LDA(At, 0, 1); PG8_STAGE(PG8_SB(0, 0), b2, voffB); PG8_STAGE(PG8_SB(0, 1), b2 + hstep, voffB); PG8_STAGE(PG8_SA(0, 0), a2, voffA);
;             PG8_WAIT_V(8); PG8_WAIT_L(0); PG8_BAR; PG8_MMA(1, 0, At, B0); PG8_MMA(1, 1, At, B1); PG8_BAR; PG8_SCHED;
	ds_read_b128 v[144:147], v151
	ds_read_b128 v[154:157], v151 offset:1024
	ds_read_b128 v[158:161], v151 offset:2048
	ds_read_b128 v[162:165], v151 offset:3072
	ds_read_b128 v[166:169], v152
	ds_read_b128 v[170:173], v152 offset:1024
	ds_read_b128 v[174:177], v152 offset:2048
	ds_read_b128 v[178:181], v152 offset:3072
	s_add_u32 s24, s22, 0xfffc0080
	s_addc_u32 s25, s23, -1
	s_cmp_eq_u32 s48, 12
	s_cselect_b32 s27, s15, s25
	s_cselect_b32 s26, s44, s24
	s_cselect_b32 s25, s13, s47
	s_cselect_b32 s24, s45, s46
	v_lshl_add_u64 v[206:207], s[22:23], 0, v[136:137]
	s_add_i32 m0, s21, 0xc000
	ds_read_b128 v[182:185], v153
	ds_read_b128 v[186:189], v153 offset:1024
	ds_read_b128 v[190:193], v153 offset:2048
	ds_read_b128 v[194:197], v153 offset:3072
	ds_read_b128 v[198:201], v153 offset:4096
	ds_read_b128 v[202:205], v153 offset:5120
	ds_read_b128 v[212:215], v153 offset:6144
	ds_read_b128 v[216:219], v153 offset:7168
	global_load_lds_dwordx4 v[206:207], off
	v_lshl_add_u64 v[206:207], s[22:23], 0, v[138:139]
	s_add_i32 m0, s21, 0xe000
	s_nop 0
	global_load_lds_dwordx4 v[206:207], off
	s_waitcnt vmcnt(8)
	s_waitcnt lgkmcnt(0)
	s_barrier
	s_setprio 1
	s_waitcnt lgkmcnt(0)
	v_mfma_f32_16x16x32_bf16 v[124:127], v[144:147], v[182:185], 0
	v_mfma_f32_16x16x32_bf16 v[116:119], v[158:161], v[182:185], 0
	v_mfma_f32_16x16x32_bf16 v[108:111], v[144:147], v[190:193], 0
	v_mfma_f32_16x16x32_bf16 v[100:103], v[158:161], v[190:193], 0
	v_mfma_f32_16x16x32_bf16 v[92:95], v[144:147], v[198:201], 0
	v_mfma_f32_16x16x32_bf16 v[84:87], v[158:161], v[198:201], 0
	v_mfma_f32_16x16x32_bf16 v[76:79], v[144:147], v[212:215], 0
	v_mfma_f32_16x16x32_bf16 v[68:71], v[158:161], v[212:215], 0
	v_mfma_f32_16x16x32_bf16 v[124:127], v[154:157], v[186:189], v[124:127]
	v_mfma_f32_16x16x32_bf16 v[116:119], v[162:165], v[186:189], v[116:119]
	v_mfma_f32_16x16x32_bf16 v[108:111], v[154:157], v[194:197], v[108:111]
	v_mfma_f32_16x16x32_bf16 v[100:103], v[162:165], v[194:197], v[100:103]
	v_mfma_f32_16x16x32_bf16 v[92:95], v[154:157], v[202:205], v[92:95]
	v_mfma_f32_16x16x32_bf16 v[84:87], v[162:165], v[202:205], v[84:87]
	v_mfma_f32_16x16x32_bf16 v[76:79], v[154:157], v[216:219], v[76:79]
	v_mfma_f32_16x16x32_bf16 v[68:71], v[162:165], v[216:219], v[68:71]
	s_setprio 0
	s_setprio 1
	v_mfma_f32_16x16x32_bf16 v[120:123], v[166:169], v[182:185], 0
	v_mfma_f32_16x16x32_bf16 v[112:115], v[174:177], v[182:185], 0
	v_mfma_f32_16x16x32_bf16 v[104:107], v[166:169], v[190:193], 0
	v_mfma_f32_16x16x32_bf16 v[96:99], v[174:177], v[190:193], 0
	v_mfma_f32_16x16x32_bf16 v[88:91], v[166:169], v[198:201], 0
	v_mfma_f32_16x16x32_bf16 v[80:83], v[174:177], v[198:201], 0
	v_mfma_f32_16x16x32_bf16 v[72:75], v[166:169], v[212:215], 0
	v_mfma_f32_16x16x32_bf16 v[64:67], v[174:177], v[212:215], 0
	v_mfma_f32_16x16x32_bf16 v[120:123], v[170:173], v[186:189], v[120:123]
	v_mfma_f32_16x16x32_bf16 v[112:115], v[178:181], v[186:189], v[112:115]
	v_mfma_f32_16x16x32_bf16 v[104:107], v[170:173], v[194:197], v[104:107]
	v_mfma_f32_16x16x32_bf16 v[96:99], v[178:181], v[194:197], v[96:99]
	v_mfma_f32_16x16x32_bf16 v[88:91], v[170:173], v[202:205], v[88:91]
	v_mfma_f32_16x16x32_bf16 v[80:83], v[178:181], v[202:205], v[80:83]
	v_mfma_f32_16x16x32_bf16 v[72:75], v[170:173], v[216:219], v[72:75]
	v_mfma_f32_16x16x32_bf16 v[64:67], v[178:181], v[216:219], v[64:67]
	s_setprio 0
	s_barrier
	s_add_i32 s49, s40, s9
	v_lshl_add_u64 v[206:207], s[24:25], 0, v[132:133]
	s_mov_b32 m0, s49
	ds_read_b128 v[182:185], v153 offset:16384
	ds_read_b128 v[186:189], v153 offset:17408
	ds_read_b128 v[190:193], v153 offset:18432
	ds_read_b128 v[194:197], v153 offset:19456
	ds_read_b128 v[198:201], v153 offset:20480
	ds_read_b128 v[202:205], v153 offset:21504
	ds_read_b128 v[212:215], v153 offset:22528
	ds_read_b128 v[216:219], v153 offset:23552
	global_load_lds_dwordx4 v[206:207], off
	s_add_i32 m0, s49, 0x2000
	s_add_u32 s50, s24, 0x40000
	v_lshl_add_u64 v[220:221], s[24:25], 0, v[128:129]
	s_addc_u32 s51, s25, 0
	s_add_i32 s49, s41, s9
	global_load_lds_dwordx4 v[220:221], off
	v_lshl_add_u64 v[222:223], s[50:51], 0, v[132:133]
	s_mov_b32 m0, s49
	v_lshl_add_u64 v[224:225], s[26:27], 0, v[130:131]
	global_load_lds_dwordx4 v[222:223], off
	v_lshl_add_u64 v[222:223], s[50:51], 0, v[128:129]
	s_add_i32 m0, s49, 0x2000
	s_nop 0
	global_load_lds_dwordx4 v[222:223], off
	v_lshl_add_u64 v[222:223], s[26:27], 0, v[134:135]
	s_mov_b32 m0, s21
	s_nop 0
	global_load_lds_dwordx4 v[222:223], off
	s_mov_b32 m0, s30
	s_nop 0
	global_load_lds_dwordx4 v[224:225], off
	s_add_u32 s88, s22, 0xfffbff80
	s_addc_u32 s89, s23, -1
	s_add_u32 s90, s46, 0xffffff00
	s_addc_u32 s91, s47, -1
	s_add_i32 s34, s34, 1
	s_mul_i32 s4, s34, s35
	s_mul_hi_u32 s5, s34, s77
	s_add_i32 s5, s5, s4
	s_mul_i32 s4, s34, s77
	s_add_u32 s16, s4, s82
	s_addc_u32 s17, s5, s28
	v_cmp_gt_i64_e32 vcc, s[16:17], v[142:143]
	v_cmp_lt_i64_e64 s[4:5], s[16:17], v[140:141]
	s_cbranch_vccnz .LBB0_268
	s_ashr_i32 s12, s16, 31
	s_lshr_b32 s12, s12, 29
	s_add_i32 s12, s16, s12
	s_ashr_i32 s13, s12, 3
	s_and_b32 s12, s12, -8
	s_sub_i32 s12, s16, s12
	s_cmp_lt_i32 s12, 0
	s_cselect_b32 s14, s29, 0xb0
	s_mul_i32 s12, s12, s14
	s_add_i32 s12, s12, s13
	s_mul_hi_i32 s13, s12, 0x2e8ba2e9
	s_lshr_b32 s14, s13, 31
	s_ashr_i32 s13, s13, 5
	s_add_i32 s13, s13, s14
	s_lshl_b32 s14, s13, 3
	s_sub_i32 s15, 64, s14
	s_min_i32 s15, s15, 8
	s_abs_i32 s16, s15
	v_cvt_f32_u32_e32 v228, s16
	s_sub_i32 s18, 0, s16
	s_mulk_i32 s13, 0xb0
	s_sub_i32 s13, s12, s13
	v_rcp_iflag_f32_e32 v228, v228
	s_abs_i32 s12, s13
	s_xor_b32 s17, s13, s15
	s_ashr_i32 s17, s17, 31
	v_mul_f32_e32 v228, 0x4f7ffffe, v228
	v_cvt_u32_f32_e32 v228, v228
	s_nop 0
	v_readfirstlane_b32 s19, v228
	s_mul_i32 s18, s18, s19
	s_mul_hi_u32 s18, s19, s18
	s_add_i32 s19, s19, s18
	s_mul_hi_u32 s18, s12, s19
	s_mul_i32 s19, s18, s16
	s_sub_i32 s12, s12, s19
	s_add_i32 s100, s18, 1
	s_sub_i32 s19, s12, s16
	s_cmp_ge_u32 s12, s16
	s_cselect_b32 s18, s100, s18
	s_cselect_b32 s12, s19, s12
	s_add_i32 s19, s18, 1
	s_cmp_ge_u32 s12, s16
	s_cselect_b32 s12, s19, s18
	s_xor_b32 s12, s12, s17
	s_sub_i32 s12, s12, s17
	s_mul_i32 s15, s12, s15
	s_sub_i32 s13, s13, s15
	s_add_i32 s14, s14, s13
; #define PG8_STAGE(bufoff, gbase, voff) do { _Pragma("unroll") for (int _i = 0; _i < 2; ++_i) \
;         __builtin_amdgcn_global_load_lds((const unsigned*)((const char*)(gbase) + (voff)[_i]), (PG8_LAS unsigned*)(lds + (bufoff) + ldsw + _i * 8192), 16, 0, 0); } while (0)
; #define PG8_LDA(dst, b, h) do { _Pragma("unroll") for (int m = 0; m < 4; ++m) _Pragma("unroll") for (int k = 0; k < 2; ++k) dst[m][k] = *(const PG8_LAS bf16x8*)(lds + PG8_SA(b, h) + aoff + m * 2048 + k * 1024); } while (0)
; #define PG8_LDB(dst, b, h) do { _Pragma("unroll") for (int n = 0; n < 2; ++n) _Pragma("unroll") for (int k = 0; k < 2; ++k) dst[n][k] = *(const PG8_LAS bf16x8*)(lds + PG8_SB(b, h) + boff + n * 2048 + k * 1024); } while (0)
; #define PG8_MMA(ai, bj, At, Bt) do { __builtin_amdgcn_s_setprio(1); _Pragma("unroll") for (int m = 0; m < 4; ++m) _Pragma("unroll") for (int n = 0; n < 2; ++n) _Pragma("unroll") for (int k = 0; k < 2; ++k) \
;         acc[ai][bj][m][n] = __builtin_amdgcn_mfma_f32_16x16x32_bf16(Bt[n][k], At[m][k], acc[ai][bj][m][n], 0, 0, 0); __builtin_amdgcn_s_setprio(0); } while (0)
; #define PG8_WAIT_V(n) asm volatile("s_waitcnt vmcnt(" #n ")" ::: "memory")
; #define PG8_WAIT_L(n) asm volatile("s_waitcnt lgkmcnt(" #n ")" ::: "memory")
; #define PG8_BAR __builtin_amdgcn_s_barrier()
; #define PG8_SCHED __builtin_amdgcn_sched_barrier(0)
; template <class Epi, class Sched, bool ALIGN_EPI = false, bool SP2 = false>
; __device__ __forceinline__ void gemm_phase(PG8_LAS unsigned char* lds, const Gemm g, const Sched& S, const Epi& E, const int wid) {
;     ...
;         const bool has_next = S.next(ui + 1, nxt);
;         const char* nA = has_next ? (const char*)g.A + (size_t)nxt.pm * tstep : cA; const char* nB = has_next ? (const char*)g.Bt + (size_t)nxt.pn * tstep : cB;
;     ...
;             PG8_WAIT_V(8); PG8_WAIT_L(0); PG8_BAR; PG8_MMA(1, 0, At, B0); PG8_MMA(1, 1, At, B1); PG8_BAR; PG8_SCHED;
;             PG8_LDB(B0, 1, 0); PG8_LDB(B1, 1, 1); PG8_SCHED; PG8_LDA(At, 1, 0); PG8_STAGE(PG8_SA(0, 1), a2 + hstep, voffA);
;             PG8_WAIT_V(8); PG8_WAIT_L(0); PG8_BAR; PG8_MMA(0, 0, At, B0); PG8_MMA(0, 1, At, B1); PG8_BAR; PG8_SCHED;
.LBB0_268:
	s_ashr_i32 s15, s14, 31
	s_lshl_b64 s[16:17], s[14:15], 19
	s_add_u32 s16, s80, s16
	s_addc_u32 s17, s81, s17
	s_and_b64 s[18:19], s[4:5], exec
	s_cselect_b32 s15, s17, s89
	s_cselect_b32 s44, s16, s88
	s_ashr_i32 s13, s12, 31
	s_lshl_b64 s[18:19], s[12:13], 19
	s_add_u32 s18, s10, s18
	s_addc_u32 s19, s11, s19
	s_and_b64 s[100:101], s[4:5], exec
	s_cselect_b32 s13, s19, s91
	s_cselect_b32 s45, s18, s90
	s_waitcnt vmcnt(8)
	s_waitcnt lgkmcnt(0)
	s_barrier
	s_setprio 1
	s_waitcnt lgkmcnt(0)
	v_mfma_f32_16x16x32_bf16 v[60:63], v[144:147], v[182:185], 0
	v_mfma_f32_16x16x32_bf16 v[52:55], v[158:161], v[182:185], 0
	v_mfma_f32_16x16x32_bf16 v[44:47], v[144:147], v[190:193], 0
	v_mfma_f32_16x16x32_bf16 v[36:39], v[158:161], v[190:193], 0
	v_mfma_f32_16x16x32_bf16 v[28:31], v[144:147], v[198:201], 0
	v_mfma_f32_16x16x32_bf16 v[20:23], v[158:161], v[198:201], 0
	v_mfma_f32_16x16x32_bf16 v[12:15], v[144:147], v[212:215], 0
	v_mfma_f32_16x16x32_bf16 v[4:7], v[158:161], v[212:215], 0
	v_mfma_f32_16x16x32_bf16 v[60:63], v[154:157], v[186:189], v[60:63]
	v_mfma_f32_16x16x32_bf16 v[52:55], v[162:165], v[186:189], v[52:55]
	v_mfma_f32_16x16x32_bf16 v[44:47], v[154:157], v[194:197], v[44:47]
	v_mfma_f32_16x16x32_bf16 v[36:39], v[162:165], v[194:197], v[36:39]
	v_mfma_f32_16x16x32_bf16 v[28:31], v[154:157], v[202:205], v[28:31]
	v_mfma_f32_16x16x32_bf16 v[20:23], v[162:165], v[202:205], v[20:23]
	v_mfma_f32_16x16x32_bf16 v[12:15], v[154:157], v[216:219], v[12:15]
	v_mfma_f32_16x16x32_bf16 v[4:7], v[162:165], v[216:219], v[4:7]
	s_setprio 0
	s_setprio 1
	v_mfma_f32_16x16x32_bf16 v[56:59], v[166:169], v[182:185], 0
	v_mfma_f32_16x16x32_bf16 v[48:51], v[174:177], v[182:185], 0
	v_mfma_f32_16x16x32_bf16 v[40:43], v[166:169], v[190:193], 0
	v_mfma_f32_16x16x32_bf16 v[32:35], v[174:177], v[190:193], 0
	v_mfma_f32_16x16x32_bf16 v[24:27], v[166:169], v[198:201], 0
	v_mfma_f32_16x16x32_bf16 v[16:19], v[174:177], v[198:201], 0
	v_mfma_f32_16x16x32_bf16 v[8:11], v[166:169], v[212:215], 0
	v_mfma_f32_16x16x32_bf16 v[0:3], v[174:177], v[212:215], 0
	v_mfma_f32_16x16x32_bf16 v[56:59], v[170:173], v[186:189], v[56:59]
	v_mfma_f32_16x16x32_bf16 v[48:51], v[178:181], v[186:189], v[48:51]
	v_mfma_f32_16x16x32_bf16 v[40:43], v[170:173], v[194:197], v[40:43]
	v_mfma_f32_16x16x32_bf16 v[32:35], v[178:181], v[194:197], v[32:35]
	v_mfma_f32_16x16x32_bf16 v[24:27], v[170:173], v[202:205], v[24:27]
	v_mfma_f32_16x16x32_bf16 v[16:19], v[178:181], v[202:205], v[16:19]
	v_mfma_f32_16x16x32_bf16 v[8:11], v[170:173], v[216:219], v[8:11]
	v_mfma_f32_16x16x32_bf16 v[0:3], v[178:181], v[216:219], v[0:3]
	s_setprio 0
	s_barrier
	s_add_i32 s49, 0, 0x18000
	s_add_i32 s50, 0, 0x1c000
	v_add_u32_e32 v162, s49, v149
	v_add_u32_e32 v178, s50, v149
	ds_read_b128 v[144:147], v162
	ds_read_b128 v[154:157], v162 offset:1024
	ds_read_b128 v[158:161], v162 offset:2048
	ds_read_b128 v[162:165], v162 offset:3072
	ds_read_b128 v[166:169], v178
	ds_read_b128 v[170:173], v178 offset:1024
	ds_read_b128 v[174:177], v178 offset:2048
	ds_read_b128 v[178:181], v178 offset:3072
	s_add_u32 s26, s26, 0x40000
	s_addc_u32 s27, s27, 0
	s_mov_b32 m0, s31
	v_lshl_add_u64 v[226:227], s[26:27], 0, v[134:135]
	ds_read_b128 v[182:185], v153 offset:32768
	ds_read_b128 v[186:189], v153 offset:33792
	ds_read_b128 v[190:193], v153 offset:34816
	ds_read_b128 v[194:197], v153 offset:35840
	ds_read_b128 v[198:201], v153 offset:36864
	ds_read_b128 v[202:205], v153 offset:37888
	ds_read_b128 v[212:215], v153 offset:38912
	ds_read_b128 v[216:219], v153 offset:39936
	global_load_lds_dwordx4 v[226:227], off
	v_lshl_add_u64 v[226:227], s[26:27], 0, v[130:131]
	s_mov_b32 m0, s33
	s_nop 0
	global_load_lds_dwordx4 v[226:227], off
	s_waitcnt vmcnt(8)
	s_waitcnt lgkmcnt(0)
	s_barrier
; #define PG8_STAGE(bufoff, gbase, voff) do { _Pragma("unroll") for (int _i = 0; _i < 2; ++_i) \
;         __builtin_amdgcn_global_load_lds((const unsigned*)((const char*)(gbase) + (voff)[_i]), (PG8_LAS unsigned*)(lds + (bufoff) + ldsw + _i * 8192), 16, 0, 0); } while (0)
; #define PG8_LDA(dst, b, h) do { _Pragma("unroll") for (int m = 0; m < 4; ++m) _Pragma("unroll") for (int k = 0; k < 2; ++k) dst[m][k] = *(const PG8_LAS bf16x8*)(lds + PG8_SA(b, h) + aoff + m * 2048 + k * 1024); } while (0)
; #define PG8_MMA(ai, bj, At, Bt) do { __builtin_amdgcn_s_setprio(1); _Pragma("unroll") for (int m = 0; m < 4; ++m) _Pragma("unroll") for (int n = 0; n < 2; ++n) _Pragma("unroll") for (int k = 0; k < 2; ++k) \
;         acc[ai][bj][m][n] = __builtin_amdgcn_mfma_f32_16x16x32_bf16(Bt[n][k], At[m][k], acc[ai][bj][m][n], 0, 0, 0); __builtin_amdgcn_s_setprio(0); } while (0)
; #define PG8_WAIT_V(n) asm volatile("s_waitcnt vmcnt(" #n ")" ::: "memory")
; #define PG8_WAIT_L(n) asm volatile("s_waitcnt lgkmcnt(" #n ")" ::: "memory")
; #define PG8_BAR __builtin_amdgcn_s_barrier()
; #define PG8_SCHED __builtin_amdgcn_sched_barrier(0)
; template <class Epi, class Sched, bool ALIGN_EPI = false, bool SP2 = false>
; __device__ __forceinline__ void gemm_phase(PG8_LAS unsigned char* lds, const Gemm g, const Sched& S, const Epi& E, const int wid) {
;     ...
;             PG8_WAIT_V(8); PG8_WAIT_L(0); PG8_BAR; PG8_MMA(0, 0, At, B0); PG8_MMA(0, 1, At, B1); PG8_BAR; PG8_SCHED;
;             PG8_LDA(At, 1, 1); PG8_STAGE(PG8_SB(1, 0), b3, voffB); PG8_STAGE(PG8_SB(1, 1), b3 + hstep, voffB); PG8_STAGE(PG8_SA(1, 0), a3, voffA);
;             PG8_WAIT_V(8); PG8_WAIT_L(0); PG8_BAR; PG8_MMA(1, 0, At, B0); PG8_MMA(1, 1, At, B1); PG8_BAR; PG8_SCHED;
	s_setprio 1
	s_waitcnt lgkmcnt(0)
	v_mfma_f32_16x16x32_bf16 v[124:127], v[144:147], v[182:185], v[124:127]
	v_mfma_f32_16x16x32_bf16 v[116:119], v[158:161], v[182:185], v[116:119]
	v_mfma_f32_16x16x32_bf16 v[108:111], v[144:147], v[190:193], v[108:111]
	v_mfma_f32_16x16x32_bf16 v[100:103], v[158:161], v[190:193], v[100:103]
	v_mfma_f32_16x16x32_bf16 v[92:95], v[144:147], v[198:201], v[92:95]
	v_mfma_f32_16x16x32_bf16 v[84:87], v[158:161], v[198:201], v[84:87]
	v_mfma_f32_16x16x32_bf16 v[76:79], v[144:147], v[212:215], v[76:79]
	v_mfma_f32_16x16x32_bf16 v[68:71], v[158:161], v[212:215], v[68:71]
	v_mfma_f32_16x16x32_bf16 v[124:127], v[154:157], v[186:189], v[124:127]
	v_mfma_f32_16x16x32_bf16 v[116:119], v[162:165], v[186:189], v[116:119]
	v_mfma_f32_16x16x32_bf16 v[108:111], v[154:157], v[194:197], v[108:111]
	v_mfma_f32_16x16x32_bf16 v[100:103], v[162:165], v[194:197], v[100:103]
	v_mfma_f32_16x16x32_bf16 v[92:95], v[154:157], v[202:205], v[92:95]
	v_mfma_f32_16x16x32_bf16 v[84:87], v[162:165], v[202:205], v[84:87]
	v_mfma_f32_16x16x32_bf16 v[76:79], v[154:157], v[216:219], v[76:79]
	v_mfma_f32_16x16x32_bf16 v[68:71], v[162:165], v[216:219], v[68:71]
	s_setprio 0
	s_setprio 1
	v_mfma_f32_16x16x32_bf16 v[120:123], v[166:169], v[182:185], v[120:123]
	v_mfma_f32_16x16x32_bf16 v[112:115], v[174:177], v[182:185], v[112:115]
	v_mfma_f32_16x16x32_bf16 v[104:107], v[166:169], v[190:193], v[104:107]
	v_mfma_f32_16x16x32_bf16 v[96:99], v[174:177], v[190:193], v[96:99]
	v_mfma_f32_16x16x32_bf16 v[88:91], v[166:169], v[198:201], v[88:91]
	v_mfma_f32_16x16x32_bf16 v[80:83], v[174:177], v[198:201], v[80:83]
	v_mfma_f32_16x16x32_bf16 v[72:75], v[166:169], v[212:215], v[72:75]
	v_mfma_f32_16x16x32_bf16 v[64:67], v[174:177], v[212:215], v[64:67]
	v_mfma_f32_16x16x32_bf16 v[120:123], v[170:173], v[186:189], v[120:123]
	v_mfma_f32_16x16x32_bf16 v[112:115], v[178:181], v[186:189], v[112:115]
	v_mfma_f32_16x16x32_bf16 v[104:107], v[170:173], v[194:197], v[104:107]
	v_mfma_f32_16x16x32_bf16 v[96:99], v[178:181], v[194:197], v[96:99]
	v_mfma_f32_16x16x32_bf16 v[88:91], v[170:173], v[202:205], v[88:91]
	v_mfma_f32_16x16x32_bf16 v[80:83], v[178:181], v[202:205], v[80:83]
	v_mfma_f32_16x16x32_bf16 v[72:75], v[170:173], v[216:219], v[72:75]
	v_mfma_f32_16x16x32_bf16 v[64:67], v[178:181], v[216:219], v[64:67]
	s_setprio 0
	s_barrier
	s_add_i32 s26, s49, s9
	v_lshl_add_u64 v[206:207], v[206:207], 0, s[6:7]
	s_mov_b32 m0, s26
	ds_read_b128 v[182:185], v153 offset:49152
	ds_read_b128 v[186:189], v153 offset:50176
	ds_read_b128 v[190:193], v153 offset:51200
	ds_read_b128 v[194:197], v153 offset:52224
	ds_read_b128 v[198:201], v153 offset:53248
	ds_read_b128 v[202:205], v153 offset:54272
	ds_read_b128 v[212:215], v153 offset:55296
	ds_read_b128 v[216:219], v153 offset:56320
	global_load_lds_dwordx4 v[206:207], off
	s_add_i32 m0, s26, 0x2000
	s_add_u32 s24, s24, 0x40080
	v_lshl_add_u64 v[206:207], v[220:221], 0, s[6:7]
	s_addc_u32 s25, s25, 0
	s_add_i32 s26, s50, s9
	global_load_lds_dwordx4 v[206:207], off
	v_lshl_add_u64 v[206:207], s[24:25], 0, v[132:133]
	s_mov_b32 m0, s26
	s_nop 0
	global_load_lds_dwordx4 v[206:207], off
	v_lshl_add_u64 v[206:207], s[24:25], 0, v[128:129]
	s_add_i32 m0, s26, 0x2000
	s_nop 0
	global_load_lds_dwordx4 v[206:207], off
	v_lshl_add_u64 v[206:207], v[222:223], 0, s[6:7]
	s_mov_b32 m0, s38
	s_nop 0
	global_load_lds_dwordx4 v[206:207], off
	v_lshl_add_u64 v[206:207], v[224:225], 0, s[6:7]
	s_mov_b32 m0, s39
	s_nop 0
	global_load_lds_dwordx4 v[206:207], off
	s_waitcnt vmcnt(8)
	s_waitcnt lgkmcnt(0)
	s_barrier
	s_setprio 1
	s_waitcnt lgkmcnt(0)
	v_mfma_f32_16x16x32_bf16 v[60:63], v[144:147], v[182:185], v[60:63]
	v_mfma_f32_16x16x32_bf16 v[52:55], v[158:161], v[182:185], v[52:55]
	v_mfma_f32_16x16x32_bf16 v[44:47], v[144:147], v[190:193], v[44:47]
	v_mfma_f32_16x16x32_bf16 v[36:39], v[158:161], v[190:193], v[36:39]
	v_mfma_f32_16x16x32_bf16 v[28:31], v[144:147], v[198:201], v[28:31]
	v_mfma_f32_16x16x32_bf16 v[20:23], v[158:161], v[198:201], v[20:23]
	v_mfma_f32_16x16x32_bf16 v[12:15], v[144:147], v[212:215], v[12:15]
	v_mfma_f32_16x16x32_bf16 v[4:7], v[158:161], v[212:215], v[4:7]
	v_mfma_f32_16x16x32_bf16 v[60:63], v[154:157], v[186:189], v[60:63]
	v_mfma_f32_16x16x32_bf16 v[52:55], v[162:165], v[186:189], v[52:55]
	v_mfma_f32_16x16x32_bf16 v[44:47], v[154:157], v[194:197], v[44:47]
	v_mfma_f32_16x16x32_bf16 v[36:39], v[162:165], v[194:197], v[36:39]
	v_mfma_f32_16x16x32_bf16 v[28:31], v[154:157], v[202:205], v[28:31]
	v_mfma_f32_16x16x32_bf16 v[20:23], v[162:165], v[202:205], v[20:23]
	v_mfma_f32_16x16x32_bf16 v[12:15], v[154:157], v[216:219], v[12:15]
	v_mfma_f32_16x16x32_bf16 v[4:7], v[162:165], v[216:219], v[4:7]
	s_setprio 0
	s_setprio 1
	v_mfma_f32_16x16x32_bf16 v[56:59], v[166:169], v[182:185], v[56:59]
	v_mfma_f32_16x16x32_bf16 v[48:51], v[174:177], v[182:185], v[48:51]
	v_mfma_f32_16x16x32_bf16 v[40:43], v[166:169], v[190:193], v[40:43]
	v_mfma_f32_16x16x32_bf16 v[32:35], v[174:177], v[190:193], v[32:35]
	v_mfma_f32_16x16x32_bf16 v[24:27], v[166:169], v[198:201], v[24:27]
	v_mfma_f32_16x16x32_bf16 v[16:19], v[174:177], v[198:201], v[16:19]
	v_mfma_f32_16x16x32_bf16 v[8:11], v[166:169], v[212:215], v[8:11]
	v_mfma_f32_16x16x32_bf16 v[0:3], v[174:177], v[212:215], v[0:3]
	v_mfma_f32_16x16x32_bf16 v[56:59], v[170:173], v[186:189], v[56:59]
	v_mfma_f32_16x16x32_bf16 v[48:51], v[178:181], v[186:189], v[48:51]
	v_mfma_f32_16x16x32_bf16 v[40:43], v[170:173], v[194:197], v[40:43]
	v_mfma_f32_16x16x32_bf16 v[32:35], v[178:181], v[194:197], v[32:35]
	v_mfma_f32_16x16x32_bf16 v[24:27], v[170:173], v[202:205], v[24:27]
	v_mfma_f32_16x16x32_bf16 v[16:19], v[178:181], v[202:205], v[16:19]
	v_mfma_f32_16x16x32_bf16 v[8:11], v[170:173], v[216:219], v[8:11]
	v_mfma_f32_16x16x32_bf16 v[0:3], v[178:181], v[216:219], v[0:3]
	s_setprio 0
	s_barrier
	s_add_i32 s48, s48, 2
	s_add_u32 s22, s22, 0x100
	s_addc_u32 s23, s23, 0
	s_add_u32 s46, s46, 0x100
	s_addc_u32 s47, s47, 0
	s_cmp_gt_u32 s48, 13
	s_cbranch_scc0 .LBB0_269
	s_branch .Lkp_exit_0

; template <class Epi, class Sched, bool ALIGN_EPI = false, bool SP2 = false>
; __device__ __forceinline__ void gemm_phase(PG8_LAS unsigned char* lds, const Gemm g, const Sched& S, const Epi& E, const int wid) {
;     ...
;         const bool has_next = S.next(ui + 1, nxt);
;         const char* nA = has_next ? (const char*)g.A + (size_t)nxt.pm * tstep : cA; const char* nB = has_next ? (const char*)g.Bt + (size_t)nxt.pn * tstep : cB;
;         for (int t = 0; t < nt; t += 2) {
;             const bool last = (t == nt - 2);
;             const char* a1 = cA + (size_t)(t + 1) * kstep;
;             const char* a2 = last ? nA : cA + (size_t)(t + 2) * kstep; const char* b2 = last ? nB : cB + (size_t)(t + 2) * kstep;
;             const char* a3 = a2 + kstep; const char* b3 = b2 + kstep;
.LBB0_879:
	s_add_u32 s20, s20, 0x40080
	s_addc_u32 s21, s21, 0
	s_add_u32 s45, s22, 0x100

; template <class Epi, class Sched, bool ALIGN_EPI = false, bool SP2 = false>
; __device__ __forceinline__ void gemm_phase(PG8_LAS unsigned char* lds, const Gemm g, const Sched& S, const Epi& E, const int wid) {
;     ...
;         for (int t = 0; t < nt; t += 2) {
;             const bool last = (t == nt - 2);
;             const char* a1 = cA + (size_t)(t + 1) * kstep;
;             const char* a2 = last ? nA : cA + (size_t)(t + 2) * kstep; const char* b2 = last ? nB : cB + (size_t)(t + 2) * kstep;
;             const char* a3 = a2 + kstep; const char* b3 = b2 + kstep;
	s_addc_u32 s46, s23, 0
	s_mov_b32 s47, -2


; #define PG8_STAGE(bufoff, gbase, voff) do { _Pragma("unroll") for (int _i = 0; _i < 2; ++_i) \
;         __builtin_amdgcn_global_load_lds((const unsigned*)((const char*)(gbase) + (voff)[_i]), (PG8_LAS unsigned*)(lds + (bufoff) + ldsw + _i * 8192), 16, 0, 0); } while (0)
; #define PG8_LDA(dst, b, h) do { _Pragma("unroll") for (int m = 0; m < 4; ++m) _Pragma("unroll") for (int k = 0; k < 2; ++k) dst[m][k] = *(const PG8_LAS bf16x8*)(lds + PG8_SA(b, h) + aoff + m * 2048 + k * 1024); } while (0)
; #define PG8_LDB(dst, b, h) do { _Pragma("unroll") for (int n = 0; n < 2; ++n) _Pragma("unroll") for (int k = 0; k < 2; ++k) dst[n][k] = *(const PG8_LAS bf16x8*)(lds + PG8_SB(b, h) + boff + n * 2048 + k * 1024); } while (0)
; #define PG8_MMA(ai, bj, At, Bt) do { __builtin_amdgcn_s_setprio(1); _Pragma("unroll") for (int m = 0; m < 4; ++m) _Pragma("unroll") for (int n = 0; n < 2; ++n) _Pragma("unroll") for (int k = 0; k < 2; ++k) \
;         acc[ai][bj][m][n] = __builtin_amdgcn_mfma_f32_16x16x32_bf16(Bt[n][k], At[m][k], acc[ai][bj][m][n], 0, 0, 0); __builtin_amdgcn_s_setprio(0); } while (0)
; #define PG8_BAR __builtin_amdgcn_s_barrier()
;     __host__ __device__ bool next(int i, Unit& u) const {
;         const long L = (long)i * G + c; if (L >= nwg) return false;
;         int wgid = (int)L; { const int q = nwg / NXCD, r = nwg % NXCD, xcd = wgid % NXCD, off = wgid / NXCD; wgid = (xcd < r ? xcd * (q + 1) : r * (q + 1) + (xcd - r) * q) + off; }
;         const int nig = WGM * nN, gid = wgid / nig, fm = gid * WGM, gsz = (nM - fm) < WGM ? (nM - fm) : WGM;
;         u.pm = fm + ((wgid % nig) % gsz); u.pn = (wgid % nig) / gsz; return true;
;     }
; template <class Epi, class Sched, bool ALIGN_EPI = false, bool SP2 = false>
; __device__ __forceinline__ void gemm_phase(PG8_LAS unsigned char* lds, const Gemm g, const Sched& S, const Epi& E, const int wid) {
;     ...
;             PG8_LDB(B0, 0, 0); PG8_LDB(B1, 0, 1); PG8_SCHED; PG8_LDA(At, 0, 0); PG8_STAGE(PG8_SA(1, 1), a1 + hstep, voffA);
;             PG8_WAIT_V(8); PG8_WAIT_L(0); PG8_BAR; PG8_MMA(0, 0, At, B0); PG8_MMA(0, 1, At, B1); PG8_BAR; PG8_SCHED;
;             PG8_LDA(At, 0, 1); PG8_STAGE(PG8_SB(0, 0), b2, voffB); PG8_STAGE(PG8_SB(0, 1), b2 + hstep, voffB); PG8_STAGE(PG8_SA(0, 0), a2, voffA);
;             PG8_WAIT_V(8); PG8_WAIT_L(0); PG8_BAR; PG8_MMA(1, 0, At, B0); PG8_MMA(1, 1, At, B1); PG8_BAR; PG8_SCHED;
	ds_read_b128 v[152:155], v149
	ds_read_b128 v[156:159], v149 offset:1024
	ds_read_b128 v[160:163], v149 offset:2048
	ds_read_b128 v[164:167], v149 offset:3072
	ds_read_b128 v[168:171], v150
	ds_read_b128 v[172:175], v150 offset:1024
	ds_read_b128 v[176:179], v150 offset:2048
	ds_read_b128 v[180:183], v150 offset:3072
	s_add_u32 s22, s20, 0xfffc0080
	s_addc_u32 s23, s21, -1
	s_cmp_eq_u32 s47, 12
	s_cselect_b32 s25, s13, s23
	s_cselect_b32 s24, s43, s22
	s_cselect_b32 s23, s9, s46
	s_cselect_b32 s22, s44, s45
	v_lshl_add_u64 v[144:145], s[20:21], 0, v[136:137]
	s_add_i32 m0, s17, 0xc000
	ds_read_b128 v[184:187], v151
	ds_read_b128 v[188:191], v151 offset:1024
	ds_read_b128 v[192:195], v151 offset:2048
	ds_read_b128 v[196:199], v151 offset:3072
	ds_read_b128 v[200:203], v151 offset:4096
	ds_read_b128 v[204:207], v151 offset:5120
	ds_read_b128 v[212:215], v151 offset:6144
	ds_read_b128 v[216:219], v151 offset:7168
	global_load_lds_dwordx4 v[144:145], off
	v_lshl_add_u64 v[144:145], s[20:21], 0, v[138:139]
	s_add_i32 m0, s17, 0xe000
	s_nop 0
	global_load_lds_dwordx4 v[144:145], off
	s_waitcnt vmcnt(8)
	s_waitcnt lgkmcnt(0)
	s_barrier
	s_setprio 1
	s_waitcnt lgkmcnt(0)
	v_mfma_f32_16x16x32_bf16 v[124:127], v[152:155], v[184:187], 0
	v_mfma_f32_16x16x32_bf16 v[120:123], v[160:163], v[184:187], 0
	v_mfma_f32_16x16x32_bf16 v[116:119], v[152:155], v[192:195], 0
	v_mfma_f32_16x16x32_bf16 v[108:111], v[160:163], v[192:195], 0
	v_mfma_f32_16x16x32_bf16 v[100:103], v[152:155], v[200:203], 0
	v_mfma_f32_16x16x32_bf16 v[92:95], v[160:163], v[200:203], 0
	v_mfma_f32_16x16x32_bf16 v[84:87], v[152:155], v[212:215], 0
	v_mfma_f32_16x16x32_bf16 v[76:79], v[160:163], v[212:215], 0
	v_mfma_f32_16x16x32_bf16 v[124:127], v[156:159], v[188:191], v[124:127]
	v_mfma_f32_16x16x32_bf16 v[120:123], v[164:167], v[188:191], v[120:123]
	v_mfma_f32_16x16x32_bf16 v[116:119], v[156:159], v[196:199], v[116:119]
	v_mfma_f32_16x16x32_bf16 v[108:111], v[164:167], v[196:199], v[108:111]
	v_mfma_f32_16x16x32_bf16 v[100:103], v[156:159], v[204:207], v[100:103]
	v_mfma_f32_16x16x32_bf16 v[92:95], v[164:167], v[204:207], v[92:95]
	v_mfma_f32_16x16x32_bf16 v[84:87], v[156:159], v[216:219], v[84:87]
	v_mfma_f32_16x16x32_bf16 v[76:79], v[164:167], v[216:219], v[76:79]
	s_setprio 0
	s_setprio 1
	v_mfma_f32_16x16x32_bf16 v[112:115], v[168:171], v[184:187], 0
	v_mfma_f32_16x16x32_bf16 v[104:107], v[176:179], v[184:187], 0
	v_mfma_f32_16x16x32_bf16 v[96:99], v[168:171], v[192:195], 0
	v_mfma_f32_16x16x32_bf16 v[88:91], v[176:179], v[192:195], 0
	v_mfma_f32_16x16x32_bf16 v[80:83], v[168:171], v[200:203], 0
	v_mfma_f32_16x16x32_bf16 v[72:75], v[176:179], v[200:203], 0
	v_mfma_f32_16x16x32_bf16 v[68:71], v[168:171], v[212:215], 0
	v_mfma_f32_16x16x32_bf16 v[64:67], v[176:179], v[212:215], 0
	v_mfma_f32_16x16x32_bf16 v[112:115], v[172:175], v[188:191], v[112:115]
	v_mfma_f32_16x16x32_bf16 v[104:107], v[180:183], v[188:191], v[104:107]
	v_mfma_f32_16x16x32_bf16 v[96:99], v[172:175], v[196:199], v[96:99]
	v_mfma_f32_16x16x32_bf16 v[88:91], v[180:183], v[196:199], v[88:91]
	v_mfma_f32_16x16x32_bf16 v[80:83], v[172:175], v[204:207], v[80:83]
	v_mfma_f32_16x16x32_bf16 v[72:75], v[180:183], v[204:207], v[72:75]
	v_mfma_f32_16x16x32_bf16 v[68:71], v[172:175], v[216:219], v[68:71]
	v_mfma_f32_16x16x32_bf16 v[64:67], v[180:183], v[216:219], v[64:67]
	s_setprio 0
	s_barrier
	s_add_i32 s48, s39, s26
	v_lshl_add_u64 v[144:145], s[22:23], 0, v[132:133]
	s_mov_b32 m0, s48
	ds_read_b128 v[184:187], v151 offset:16384
	ds_read_b128 v[188:191], v151 offset:17408
	ds_read_b128 v[192:195], v151 offset:18432
	ds_read_b128 v[196:199], v151 offset:19456
	ds_read_b128 v[200:203], v151 offset:20480
	ds_read_b128 v[204:207], v151 offset:21504
	ds_read_b128 v[212:215], v151 offset:22528
	ds_read_b128 v[216:219], v151 offset:23552
	global_load_lds_dwordx4 v[144:145], off
	s_add_i32 m0, s48, 0x2000
	s_add_u32 s48, s22, 0x40000
	v_lshl_add_u64 v[220:221], s[22:23], 0, v[128:129]
	s_addc_u32 s49, s23, 0
	s_add_i32 s50, s40, s26
	global_load_lds_dwordx4 v[220:221], off
	v_lshl_add_u64 v[222:223], s[48:49], 0, v[132:133]
	s_mov_b32 m0, s50
	v_lshl_add_u64 v[224:225], s[24:25], 0, v[130:131]
	global_load_lds_dwordx4 v[222:223], off
	v_lshl_add_u64 v[222:223], s[48:49], 0, v[128:129]
	s_add_i32 m0, s50, 0x2000
	s_nop 0
	global_load_lds_dwordx4 v[222:223], off
	v_lshl_add_u64 v[222:223], s[24:25], 0, v[134:135]
	s_mov_b32 m0, s17
	s_nop 0
	global_load_lds_dwordx4 v[222:223], off
	s_mov_b32 m0, s29
	s_nop 0
	global_load_lds_dwordx4 v[224:225], off
	s_add_u32 s88, s20, 0xfffbff80
	s_addc_u32 s89, s21, -1
	s_add_u32 s90, s45, 0xffffff00
	s_addc_u32 s91, s46, -1
	s_add_i32 s33, s33, 1
	s_mul_i32 s4, s33, s36
	s_mul_hi_u32 s5, s33, s77
	s_add_i32 s5, s5, s4
	s_mul_i32 s4, s33, s77
	s_add_u32 s14, s4, s82
	s_addc_u32 s15, s5, s27
	v_cmp_gt_i64_e32 vcc, s[14:15], v[142:143]
	v_cmp_lt_i64_e64 s[4:5], s[14:15], v[140:141]
	s_cbranch_vccnz .LBB0_881
	s_ashr_i32 s8, s14, 31
	s_lshr_b32 s8, s8, 29
	s_add_i32 s8, s14, s8
	s_ashr_i32 s9, s8, 3
	s_and_b32 s8, s8, -8
	s_sub_i32 s8, s14, s8
	s_cmp_lt_i32 s8, 0
	s_cselect_b32 s12, s28, 0x70
	s_mul_i32 s8, s8, s12
	s_add_i32 s8, s8, s9
	s_mul_hi_i32 s9, s8, 0x92492493
	s_add_i32 s9, s9, s8
	s_lshr_b32 s12, s9, 31
	s_ashr_i32 s9, s9, 6
	s_add_i32 s9, s9, s12
	s_lshl_b32 s12, s9, 3
	s_sub_i32 s13, 64, s12
	s_min_i32 s13, s13, 8
	s_abs_i32 s14, s13
	v_cvt_f32_u32_e32 v228, s14
	s_sub_i32 s18, 0, s14
	s_mulk_i32 s9, 0x70
	s_sub_i32 s9, s8, s9
	v_rcp_iflag_f32_e32 v228, v228
	s_abs_i32 s8, s9
	s_xor_b32 s15, s9, s13
	s_ashr_i32 s15, s15, 31
	v_mul_f32_e32 v228, 0x4f7ffffe, v228
	v_cvt_u32_f32_e32 v228, v228
	s_nop 0
	v_readfirstlane_b32 s19, v228
	s_mul_i32 s18, s18, s19
	s_mul_hi_u32 s18, s19, s18
	s_add_i32 s19, s19, s18
	s_mul_hi_u32 s18, s8, s19
	s_mul_i32 s19, s18, s14
	s_sub_i32 s8, s8, s19
	s_add_i32 s100, s18, 1
	s_sub_i32 s19, s8, s14
	s_cmp_ge_u32 s8, s14
	s_cselect_b32 s18, s100, s18
	s_cselect_b32 s8, s19, s8
	s_add_i32 s19, s18, 1
	s_cmp_ge_u32 s8, s14
	s_cselect_b32 s8, s19, s18
	s_xor_b32 s8, s8, s15
	s_sub_i32 s8, s8, s15
	s_mul_i32 s13, s8, s13
	s_sub_i32 s9, s9, s13
	s_add_i32 s12, s12, s9
; #define PG8_STAGE(bufoff, gbase, voff) do { _Pragma("unroll") for (int _i = 0; _i < 2; ++_i) \
;         __builtin_amdgcn_global_load_lds((const unsigned*)((const char*)(gbase) + (voff)[_i]), (PG8_LAS unsigned*)(lds + (bufoff) + ldsw + _i * 8192), 16, 0, 0); } while (0)
; #define PG8_LDA(dst, b, h) do { _Pragma("unroll") for (int m = 0; m < 4; ++m) _Pragma("unroll") for (int k = 0; k < 2; ++k) dst[m][k] = *(const PG8_LAS bf16x8*)(lds + PG8_SA(b, h) + aoff + m * 2048 + k * 1024); } while (0)
; #define PG8_LDB(dst, b, h) do { _Pragma("unroll") for (int n = 0; n < 2; ++n) _Pragma("unroll") for (int k = 0; k < 2; ++k) dst[n][k] = *(const PG8_LAS bf16x8*)(lds + PG8_SB(b, h) + boff + n * 2048 + k * 1024); } while (0)
; #define PG8_MMA(ai, bj, At, Bt) do { __builtin_amdgcn_s_setprio(1); _Pragma("unroll") for (int m = 0; m < 4; ++m) _Pragma("unroll") for (int n = 0; n < 2; ++n) _Pragma("unroll") for (int k = 0; k < 2; ++k) \
;         acc[ai][bj][m][n] = __builtin_amdgcn_mfma_f32_16x16x32_bf16(Bt[n][k], At[m][k], acc[ai][bj][m][n], 0, 0, 0); __builtin_amdgcn_s_setprio(0); } while (0)
; #define PG8_WAIT_V(n) asm volatile("s_waitcnt vmcnt(" #n ")" ::: "memory")
; #define PG8_WAIT_L(n) asm volatile("s_waitcnt lgkmcnt(" #n ")" ::: "memory")
; #define PG8_BAR __builtin_amdgcn_s_barrier()
; #define PG8_SCHED __builtin_amdgcn_sched_barrier(0)
; template <class Epi, class Sched, bool ALIGN_EPI = false, bool SP2 = false>
; __device__ __forceinline__ void gemm_phase(PG8_LAS unsigned char* lds, const Gemm g, const Sched& S, const Epi& E, const int wid) {
;     ...
;         const bool has_next = S.next(ui + 1, nxt);
;         const char* nA = has_next ? (const char*)g.A + (size_t)nxt.pm * tstep : cA; const char* nB = has_next ? (const char*)g.Bt + (size_t)nxt.pn * tstep : cB;
;     ...
;             PG8_WAIT_V(8); PG8_WAIT_L(0); PG8_BAR; PG8_MMA(1, 0, At, B0); PG8_MMA(1, 1, At, B1); PG8_BAR; PG8_SCHED;
;             PG8_LDB(B0, 1, 0); PG8_LDB(B1, 1, 1); PG8_SCHED; PG8_LDA(At, 1, 0); PG8_STAGE(PG8_SA(0, 1), a2 + hstep, voffA);
;             PG8_WAIT_V(8); PG8_WAIT_L(0); PG8_BAR; PG8_MMA(0, 0, At, B0); PG8_MMA(0, 1, At, B1); PG8_BAR; PG8_SCHED;
.LBB0_881:
	s_ashr_i32 s13, s12, 31
	s_lshl_b64 s[14:15], s[12:13], 19
	s_add_u32 s14, s80, s14
	s_addc_u32 s15, s81, s15
	s_and_b64 s[18:19], s[4:5], exec
	s_cselect_b32 s13, s15, s89
	s_cselect_b32 s43, s14, s88
	s_ashr_i32 s9, s8, 31
	s_lshl_b64 s[18:19], s[8:9], 19
	s_add_u32 s18, s10, s18
	s_addc_u32 s19, s11, s19
	s_and_b64 s[100:101], s[4:5], exec
	s_cselect_b32 s9, s19, s91
	s_cselect_b32 s44, s18, s90
	s_waitcnt vmcnt(8)
	s_waitcnt lgkmcnt(0)
	s_barrier
	s_setprio 1
	s_waitcnt lgkmcnt(0)
	v_mfma_f32_16x16x32_bf16 v[60:63], v[152:155], v[184:187], 0
	v_mfma_f32_16x16x32_bf16 v[56:59], v[160:163], v[184:187], 0
	v_mfma_f32_16x16x32_bf16 v[52:55], v[152:155], v[192:195], 0
	v_mfma_f32_16x16x32_bf16 v[44:47], v[160:163], v[192:195], 0
	v_mfma_f32_16x16x32_bf16 v[36:39], v[152:155], v[200:203], 0
	v_mfma_f32_16x16x32_bf16 v[28:31], v[160:163], v[200:203], 0
	v_mfma_f32_16x16x32_bf16 v[20:23], v[152:155], v[212:215], 0
	v_mfma_f32_16x16x32_bf16 v[12:15], v[160:163], v[212:215], 0
	v_mfma_f32_16x16x32_bf16 v[60:63], v[156:159], v[188:191], v[60:63]
	v_mfma_f32_16x16x32_bf16 v[56:59], v[164:167], v[188:191], v[56:59]
	v_mfma_f32_16x16x32_bf16 v[52:55], v[156:159], v[196:199], v[52:55]
	v_mfma_f32_16x16x32_bf16 v[44:47], v[164:167], v[196:199], v[44:47]
	v_mfma_f32_16x16x32_bf16 v[36:39], v[156:159], v[204:207], v[36:39]
	v_mfma_f32_16x16x32_bf16 v[28:31], v[164:167], v[204:207], v[28:31]
	v_mfma_f32_16x16x32_bf16 v[20:23], v[156:159], v[216:219], v[20:23]
	v_mfma_f32_16x16x32_bf16 v[12:15], v[164:167], v[216:219], v[12:15]
	s_setprio 0
	s_setprio 1
	v_mfma_f32_16x16x32_bf16 v[48:51], v[168:171], v[184:187], 0
	v_mfma_f32_16x16x32_bf16 v[40:43], v[176:179], v[184:187], 0
	v_mfma_f32_16x16x32_bf16 v[32:35], v[168:171], v[192:195], 0
	v_mfma_f32_16x16x32_bf16 v[24:27], v[176:179], v[192:195], 0
	v_mfma_f32_16x16x32_bf16 v[16:19], v[168:171], v[200:203], 0
	v_mfma_f32_16x16x32_bf16 v[8:11], v[176:179], v[200:203], 0
	v_mfma_f32_16x16x32_bf16 v[4:7], v[168:171], v[212:215], 0
	v_mfma_f32_16x16x32_bf16 v[0:3], v[176:179], v[212:215], 0
	v_mfma_f32_16x16x32_bf16 v[48:51], v[172:175], v[188:191], v[48:51]
	v_mfma_f32_16x16x32_bf16 v[40:43], v[180:183], v[188:191], v[40:43]
	v_mfma_f32_16x16x32_bf16 v[32:35], v[172:175], v[196:199], v[32:35]
	v_mfma_f32_16x16x32_bf16 v[24:27], v[180:183], v[196:199], v[24:27]
	v_mfma_f32_16x16x32_bf16 v[16:19], v[172:175], v[204:207], v[16:19]
	v_mfma_f32_16x16x32_bf16 v[8:11], v[180:183], v[204:207], v[8:11]
	v_mfma_f32_16x16x32_bf16 v[4:7], v[172:175], v[216:219], v[4:7]
	v_mfma_f32_16x16x32_bf16 v[0:3], v[180:183], v[216:219], v[0:3]
	s_setprio 0
	s_barrier
	s_add_i32 s48, 0, 0x18000
	s_add_i32 s49, 0, 0x1c000
	v_add_u32_e32 v164, s48, v147
	v_add_u32_e32 v180, s49, v147
	ds_read_b128 v[152:155], v164
	ds_read_b128 v[156:159], v164 offset:1024
	ds_read_b128 v[160:163], v164 offset:2048
	ds_read_b128 v[164:167], v164 offset:3072
	ds_read_b128 v[168:171], v180
	ds_read_b128 v[172:175], v180 offset:1024
	ds_read_b128 v[176:179], v180 offset:2048
	ds_read_b128 v[180:183], v180 offset:3072
	s_add_u32 s24, s24, 0x40000
	s_addc_u32 s25, s25, 0
	s_mov_b32 m0, s30
	v_lshl_add_u64 v[226:227], s[24:25], 0, v[134:135]
	ds_read_b128 v[184:187], v151 offset:32768
	ds_read_b128 v[188:191], v151 offset:33792
	ds_read_b128 v[192:195], v151 offset:34816
	ds_read_b128 v[196:199], v151 offset:35840
	ds_read_b128 v[200:203], v151 offset:36864
	ds_read_b128 v[204:207], v151 offset:37888
	ds_read_b128 v[212:215], v151 offset:38912
	ds_read_b128 v[216:219], v151 offset:39936
	global_load_lds_dwordx4 v[226:227], off
	v_lshl_add_u64 v[226:227], s[24:25], 0, v[130:131]
	s_mov_b32 m0, s31
	s_nop 0
	global_load_lds_dwordx4 v[226:227], off
	s_waitcnt vmcnt(8)
	s_waitcnt lgkmcnt(0)
	s_barrier
; #define PG8_STAGE(bufoff, gbase, voff) do { _Pragma("unroll") for (int _i = 0; _i < 2; ++_i) \
;         __builtin_amdgcn_global_load_lds((const unsigned*)((const char*)(gbase) + (voff)[_i]), (PG8_LAS unsigned*)(lds + (bufoff) + ldsw + _i * 8192), 16, 0, 0); } while (0)
; #define PG8_LDA(dst, b, h) do { _Pragma("unroll") for (int m = 0; m < 4; ++m) _Pragma("unroll") for (int k = 0; k < 2; ++k) dst[m][k] = *(const PG8_LAS bf16x8*)(lds + PG8_SA(b, h) + aoff + m * 2048 + k * 1024); } while (0)
; #define PG8_MMA(ai, bj, At, Bt) do { __builtin_amdgcn_s_setprio(1); _Pragma("unroll") for (int m = 0; m < 4; ++m) _Pragma("unroll") for (int n = 0; n < 2; ++n) _Pragma("unroll") for (int k = 0; k < 2; ++k) \
;         acc[ai][bj][m][n] = __builtin_amdgcn_mfma_f32_16x16x32_bf16(Bt[n][k], At[m][k], acc[ai][bj][m][n], 0, 0, 0); __builtin_amdgcn_s_setprio(0); } while (0)
; #define PG8_WAIT_V(n) asm volatile("s_waitcnt vmcnt(" #n ")" ::: "memory")
; #define PG8_WAIT_L(n) asm volatile("s_waitcnt lgkmcnt(" #n ")" ::: "memory")
; #define PG8_BAR __builtin_amdgcn_s_barrier()
; #define PG8_SCHED __builtin_amdgcn_sched_barrier(0)
; template <class Epi, class Sched, bool ALIGN_EPI = false, bool SP2 = false>
; __device__ __forceinline__ void gemm_phase(PG8_LAS unsigned char* lds, const Gemm g, const Sched& S, const Epi& E, const int wid) {
;     ...
;             PG8_WAIT_V(8); PG8_WAIT_L(0); PG8_BAR; PG8_MMA(0, 0, At, B0); PG8_MMA(0, 1, At, B1); PG8_BAR; PG8_SCHED;
;             PG8_LDA(At, 1, 1); PG8_STAGE(PG8_SB(1, 0), b3, voffB); PG8_STAGE(PG8_SB(1, 1), b3 + hstep, voffB); PG8_STAGE(PG8_SA(1, 0), a3, voffA);
;             PG8_WAIT_V(8); PG8_WAIT_L(0); PG8_BAR; PG8_MMA(1, 0, At, B0); PG8_MMA(1, 1, At, B1); PG8_BAR; PG8_SCHED;
	s_setprio 1
	s_waitcnt lgkmcnt(0)
	v_mfma_f32_16x16x32_bf16 v[124:127], v[152:155], v[184:187], v[124:127]
	v_mfma_f32_16x16x32_bf16 v[120:123], v[160:163], v[184:187], v[120:123]
	v_mfma_f32_16x16x32_bf16 v[116:119], v[152:155], v[192:195], v[116:119]
	v_mfma_f32_16x16x32_bf16 v[108:111], v[160:163], v[192:195], v[108:111]
	v_mfma_f32_16x16x32_bf16 v[100:103], v[152:155], v[200:203], v[100:103]
	v_mfma_f32_16x16x32_bf16 v[92:95], v[160:163], v[200:203], v[92:95]
	v_mfma_f32_16x16x32_bf16 v[84:87], v[152:155], v[212:215], v[84:87]
	v_mfma_f32_16x16x32_bf16 v[76:79], v[160:163], v[212:215], v[76:79]
	v_mfma_f32_16x16x32_bf16 v[124:127], v[156:159], v[188:191], v[124:127]
	v_mfma_f32_16x16x32_bf16 v[120:123], v[164:167], v[188:191], v[120:123]
	v_mfma_f32_16x16x32_bf16 v[116:119], v[156:159], v[196:199], v[116:119]
	v_mfma_f32_16x16x32_bf16 v[108:111], v[164:167], v[196:199], v[108:111]
	v_mfma_f32_16x16x32_bf16 v[100:103], v[156:159], v[204:207], v[100:103]
	v_mfma_f32_16x16x32_bf16 v[92:95], v[164:167], v[204:207], v[92:95]
	v_mfma_f32_16x16x32_bf16 v[84:87], v[156:159], v[216:219], v[84:87]
	v_mfma_f32_16x16x32_bf16 v[76:79], v[164:167], v[216:219], v[76:79]
	s_setprio 0
	s_setprio 1
	v_mfma_f32_16x16x32_bf16 v[112:115], v[168:171], v[184:187], v[112:115]
	v_mfma_f32_16x16x32_bf16 v[104:107], v[176:179], v[184:187], v[104:107]
	v_mfma_f32_16x16x32_bf16 v[96:99], v[168:171], v[192:195], v[96:99]
	v_mfma_f32_16x16x32_bf16 v[88:91], v[176:179], v[192:195], v[88:91]
	v_mfma_f32_16x16x32_bf16 v[80:83], v[168:171], v[200:203], v[80:83]
	v_mfma_f32_16x16x32_bf16 v[72:75], v[176:179], v[200:203], v[72:75]
	v_mfma_f32_16x16x32_bf16 v[68:71], v[168:171], v[212:215], v[68:71]
	v_mfma_f32_16x16x32_bf16 v[64:67], v[176:179], v[212:215], v[64:67]
	v_mfma_f32_16x16x32_bf16 v[112:115], v[172:175], v[188:191], v[112:115]
	v_mfma_f32_16x16x32_bf16 v[104:107], v[180:183], v[188:191], v[104:107]
	v_mfma_f32_16x16x32_bf16 v[96:99], v[172:175], v[196:199], v[96:99]
	v_mfma_f32_16x16x32_bf16 v[88:91], v[180:183], v[196:199], v[88:91]
	v_mfma_f32_16x16x32_bf16 v[80:83], v[172:175], v[204:207], v[80:83]
	v_mfma_f32_16x16x32_bf16 v[72:75], v[180:183], v[204:207], v[72:75]
	v_mfma_f32_16x16x32_bf16 v[68:71], v[172:175], v[216:219], v[68:71]
	v_mfma_f32_16x16x32_bf16 v[64:67], v[180:183], v[216:219], v[64:67]
	s_setprio 0
	s_barrier
	s_add_i32 s24, s48, s26
	v_lshl_add_u64 v[144:145], v[144:145], 0, s[6:7]
	s_mov_b32 m0, s24
	ds_read_b128 v[184:187], v151 offset:49152
	ds_read_b128 v[188:191], v151 offset:50176
	ds_read_b128 v[192:195], v151 offset:51200
	ds_read_b128 v[196:199], v151 offset:52224
	ds_read_b128 v[200:203], v151 offset:53248
	ds_read_b128 v[204:207], v151 offset:54272
	ds_read_b128 v[212:215], v151 offset:55296
	ds_read_b128 v[216:219], v151 offset:56320
	global_load_lds_dwordx4 v[144:145], off
	s_add_i32 m0, s24, 0x2000
	s_add_u32 s22, s22, 0x40080
	v_lshl_add_u64 v[144:145], v[220:221], 0, s[6:7]
	s_addc_u32 s23, s23, 0
	s_add_i32 s24, s49, s26
	global_load_lds_dwordx4 v[144:145], off
	v_lshl_add_u64 v[144:145], s[22:23], 0, v[132:133]
	s_mov_b32 m0, s24
	s_nop 0
	global_load_lds_dwordx4 v[144:145], off
	v_lshl_add_u64 v[144:145], s[22:23], 0, v[128:129]
	s_add_i32 m0, s24, 0x2000
	s_nop 0
	global_load_lds_dwordx4 v[144:145], off
	v_lshl_add_u64 v[144:145], v[222:223], 0, s[6:7]
	s_mov_b32 m0, s37
	s_nop 0
	global_load_lds_dwordx4 v[144:145], off
	v_lshl_add_u64 v[144:145], v[224:225], 0, s[6:7]
	s_mov_b32 m0, s38
	s_nop 0
	global_load_lds_dwordx4 v[144:145], off
	s_waitcnt vmcnt(8)
	s_waitcnt lgkmcnt(0)
	s_barrier
	s_setprio 1
	s_waitcnt lgkmcnt(0)
	v_mfma_f32_16x16x32_bf16 v[60:63], v[152:155], v[184:187], v[60:63]
	v_mfma_f32_16x16x32_bf16 v[56:59], v[160:163], v[184:187], v[56:59]
	v_mfma_f32_16x16x32_bf16 v[52:55], v[152:155], v[192:195], v[52:55]
	v_mfma_f32_16x16x32_bf16 v[44:47], v[160:163], v[192:195], v[44:47]
	v_mfma_f32_16x16x32_bf16 v[36:39], v[152:155], v[200:203], v[36:39]
	v_mfma_f32_16x16x32_bf16 v[28:31], v[160:163], v[200:203], v[28:31]
	v_mfma_f32_16x16x32_bf16 v[20:23], v[152:155], v[212:215], v[20:23]
	v_mfma_f32_16x16x32_bf16 v[12:15], v[160:163], v[212:215], v[12:15]
	v_mfma_f32_16x16x32_bf16 v[60:63], v[156:159], v[188:191], v[60:63]
	v_mfma_f32_16x16x32_bf16 v[56:59], v[164:167], v[188:191], v[56:59]
	v_mfma_f32_16x16x32_bf16 v[52:55], v[156:159], v[196:199], v[52:55]
	v_mfma_f32_16x16x32_bf16 v[44:47], v[164:167], v[196:199], v[44:47]
	v_mfma_f32_16x16x32_bf16 v[36:39], v[156:159], v[204:207], v[36:39]
	v_mfma_f32_16x16x32_bf16 v[28:31], v[164:167], v[204:207], v[28:31]
	v_mfma_f32_16x16x32_bf16 v[20:23], v[156:159], v[216:219], v[20:23]
	v_mfma_f32_16x16x32_bf16 v[12:15], v[164:167], v[216:219], v[12:15]
	s_setprio 0
	s_setprio 1
	v_mfma_f32_16x16x32_bf16 v[48:51], v[168:171], v[184:187], v[48:51]
	v_mfma_f32_16x16x32_bf16 v[40:43], v[176:179], v[184:187], v[40:43]
	v_mfma_f32_16x16x32_bf16 v[32:35], v[168:171], v[192:195], v[32:35]
	v_mfma_f32_16x16x32_bf16 v[24:27], v[176:179], v[192:195], v[24:27]
	v_mfma_f32_16x16x32_bf16 v[16:19], v[168:171], v[200:203], v[16:19]
	v_mfma_f32_16x16x32_bf16 v[8:11], v[176:179], v[200:203], v[8:11]
	v_mfma_f32_16x16x32_bf16 v[4:7], v[168:171], v[212:215], v[4:7]
	v_mfma_f32_16x16x32_bf16 v[0:3], v[176:179], v[212:215], v[0:3]
	v_mfma_f32_16x16x32_bf16 v[48:51], v[172:175], v[188:191], v[48:51]
	v_mfma_f32_16x16x32_bf16 v[40:43], v[180:183], v[188:191], v[40:43]
	v_mfma_f32_16x16x32_bf16 v[32:35], v[172:175], v[196:199], v[32:35]
	v_mfma_f32_16x16x32_bf16 v[24:27], v[180:183], v[196:199], v[24:27]
	v_mfma_f32_16x16x32_bf16 v[16:19], v[172:175], v[204:207], v[16:19]
	v_mfma_f32_16x16x32_bf16 v[8:11], v[180:183], v[204:207], v[8:11]
	v_mfma_f32_16x16x32_bf16 v[4:7], v[172:175], v[216:219], v[4:7]
	v_mfma_f32_16x16x32_bf16 v[0:3], v[180:183], v[216:219], v[0:3]
	s_setprio 0
	s_barrier
	s_add_i32 s47, s47, 2
	s_add_u32 s20, s20, 0x100
	s_addc_u32 s21, s21, 0
	s_add_u32 s45, s45, 0x100
	s_addc_u32 s46, s46, 0
	s_cmp_gt_u32 s47, 13
	s_cbranch_scc0 .LBB0_882
	s_branch .Lkp_exit_2

; template <class Epi, class Sched, bool ALIGN_EPI = false, bool SP2 = false>
; __device__ __forceinline__ void gemm_phase(PG8_LAS unsigned char* lds, const Gemm g, const Sched& S, const Epi& E, const int wid) {
;     ...
;         const bool has_next = S.next(ui + 1, nxt);
;         const char* nA = has_next ? (const char*)g.A + (size_t)nxt.pm * tstep : cA; const char* nB = has_next ? (const char*)g.Bt + (size_t)nxt.pn * tstep : cB;
;         for (int t = 0; t < nt; t += 2) {
;             const bool last = (t == nt - 2);
;             const char* a1 = cA + (size_t)(t + 1) * kstep;
;             const char* a2 = last ? nA : cA + (size_t)(t + 2) * kstep; const char* b2 = last ? nB : cB + (size_t)(t + 2) * kstep;
;             const char* a3 = a2 + kstep; const char* b3 = b2 + kstep;
.LBB0_1909:
	s_add_u32 s22, s22, 0x40080
	s_addc_u32 s23, s23, 0
	s_add_u32 s44, s24, 0x100

; template <class Epi, class Sched, bool ALIGN_EPI = false, bool SP2 = false>
; __device__ __forceinline__ void gemm_phase(PG8_LAS unsigned char* lds, const Gemm g, const Sched& S, const Epi& E, const int wid) {
;     ...
;         for (int t = 0; t < nt; t += 2) {
;             const bool last = (t == nt - 2);
;             const char* a1 = cA + (size_t)(t + 1) * kstep;
;             const char* a2 = last ? nA : cA + (size_t)(t + 2) * kstep; const char* b2 = last ? nB : cB + (size_t)(t + 2) * kstep;
;             const char* a3 = a2 + kstep; const char* b3 = b2 + kstep;
	s_addc_u32 s45, s25, 0
	s_mov_b32 s46, -2


; #define PG8_STAGE(bufoff, gbase, voff) do { _Pragma("unroll") for (int _i = 0; _i < 2; ++_i) \
;         __builtin_amdgcn_global_load_lds((const unsigned*)((const char*)(gbase) + (voff)[_i]), (PG8_LAS unsigned*)(lds + (bufoff) + ldsw + _i * 8192), 16, 0, 0); } while (0)
; #define PG8_LDA(dst, b, h) do { _Pragma("unroll") for (int m = 0; m < 4; ++m) _Pragma("unroll") for (int k = 0; k < 2; ++k) dst[m][k] = *(const PG8_LAS bf16x8*)(lds + PG8_SA(b, h) + aoff + m * 2048 + k * 1024); } while (0)
; #define PG8_LDB(dst, b, h) do { _Pragma("unroll") for (int n = 0; n < 2; ++n) _Pragma("unroll") for (int k = 0; k < 2; ++k) dst[n][k] = *(const PG8_LAS bf16x8*)(lds + PG8_SB(b, h) + boff + n * 2048 + k * 1024); } while (0)
; #define PG8_MMA(ai, bj, At, Bt) do { __builtin_amdgcn_s_setprio(1); _Pragma("unroll") for (int m = 0; m < 4; ++m) _Pragma("unroll") for (int n = 0; n < 2; ++n) _Pragma("unroll") for (int k = 0; k < 2; ++k) \
;         acc[ai][bj][m][n] = __builtin_amdgcn_mfma_f32_16x16x32_bf16(Bt[n][k], At[m][k], acc[ai][bj][m][n], 0, 0, 0); __builtin_amdgcn_s_setprio(0); } while (0)
; #define PG8_WAIT_V(n) asm volatile("s_waitcnt vmcnt(" #n ")" ::: "memory")
; #define PG8_WAIT_L(n) asm volatile("s_waitcnt lgkmcnt(" #n ")" ::: "memory")
;     __host__ __device__ bool next(int i, Unit& u) const {
;         const long L = (long)i * G + c; if (L >= nwg) return false;
;         int wgid = (int)L; { const int q = nwg / NXCD, r = nwg % NXCD, xcd = wgid % NXCD, off = wgid / NXCD; wgid = (xcd < r ? xcd * (q + 1) : r * (q + 1) + (xcd - r) * q) + off; }
;         const int nig = WGM * nN, gid = wgid / nig, fm = gid * WGM, gsz = (nM - fm) < WGM ? (nM - fm) : WGM;
;         u.pm = fm + ((wgid % nig) % gsz); u.pn = (wgid % nig) / gsz; return true;
; template <class Epi, class Sched, bool ALIGN_EPI = false, bool SP2 = false>
; __device__ __forceinline__ void gemm_phase(PG8_LAS unsigned char* lds, const Gemm g, const Sched& S, const Epi& E, const int wid) {
;     ...
;             PG8_LDB(B0, 0, 0); PG8_LDB(B1, 0, 1); PG8_SCHED; PG8_LDA(At, 0, 0); PG8_STAGE(PG8_SA(1, 1), a1 + hstep, voffA);
;             PG8_WAIT_V(8); PG8_WAIT_L(0); PG8_BAR; PG8_MMA(0, 0, At, B0); PG8_MMA(0, 1, At, B1); PG8_BAR; PG8_SCHED;
;             PG8_LDA(At, 0, 1); PG8_STAGE(PG8_SB(0, 0), b2, voffB); PG8_STAGE(PG8_SB(0, 1), b2 + hstep, voffB); PG8_STAGE(PG8_SA(0, 0), a2, voffA);
	ds_read_b128 v[144:147], v151
	ds_read_b128 v[154:157], v151 offset:1024
	ds_read_b128 v[158:161], v151 offset:2048
	ds_read_b128 v[162:165], v151 offset:3072
	ds_read_b128 v[166:169], v152
	ds_read_b128 v[170:173], v152 offset:1024
	ds_read_b128 v[174:177], v152 offset:2048
	ds_read_b128 v[178:181], v152 offset:3072
	s_add_u32 s24, s22, 0xfffc0080
	s_addc_u32 s25, s23, -1
	s_cmp_eq_u32 s46, 12
	s_cselect_b32 s27, s15, s25
	s_cselect_b32 s26, s42, s24
	s_cselect_b32 s25, s13, s45
	s_cselect_b32 s24, s43, s44
	v_lshl_add_u64 v[206:207], s[22:23], 0, v[136:137]
	s_add_i32 m0, s21, 0xc000
	ds_read_b128 v[182:185], v153
	ds_read_b128 v[186:189], v153 offset:1024
	ds_read_b128 v[190:193], v153 offset:2048
	ds_read_b128 v[194:197], v153 offset:3072
	ds_read_b128 v[198:201], v153 offset:4096
	ds_read_b128 v[202:205], v153 offset:5120
	ds_read_b128 v[210:213], v153 offset:6144
	ds_read_b128 v[214:217], v153 offset:7168
	global_load_lds_dwordx4 v[206:207], off
	v_lshl_add_u64 v[206:207], s[22:23], 0, v[138:139]
	s_add_i32 m0, s21, 0xe000
	s_nop 0
	global_load_lds_dwordx4 v[206:207], off
	s_waitcnt vmcnt(8)
	s_waitcnt lgkmcnt(0)
	s_barrier
	s_setprio 1
	s_waitcnt lgkmcnt(0)
	v_mfma_f32_16x16x32_bf16 v[124:127], v[144:147], v[182:185], 0
	v_mfma_f32_16x16x32_bf16 v[116:119], v[158:161], v[182:185], 0
	v_mfma_f32_16x16x32_bf16 v[108:111], v[144:147], v[190:193], 0
	v_mfma_f32_16x16x32_bf16 v[100:103], v[158:161], v[190:193], 0
	v_mfma_f32_16x16x32_bf16 v[92:95], v[144:147], v[198:201], 0
	v_mfma_f32_16x16x32_bf16 v[84:87], v[158:161], v[198:201], 0
	v_mfma_f32_16x16x32_bf16 v[76:79], v[144:147], v[210:213], 0
	v_mfma_f32_16x16x32_bf16 v[68:71], v[158:161], v[210:213], 0
	v_mfma_f32_16x16x32_bf16 v[124:127], v[154:157], v[186:189], v[124:127]
	v_mfma_f32_16x16x32_bf16 v[116:119], v[162:165], v[186:189], v[116:119]
	v_mfma_f32_16x16x32_bf16 v[108:111], v[154:157], v[194:197], v[108:111]
	v_mfma_f32_16x16x32_bf16 v[100:103], v[162:165], v[194:197], v[100:103]
	v_mfma_f32_16x16x32_bf16 v[92:95], v[154:157], v[202:205], v[92:95]
	v_mfma_f32_16x16x32_bf16 v[84:87], v[162:165], v[202:205], v[84:87]
	v_mfma_f32_16x16x32_bf16 v[76:79], v[154:157], v[214:217], v[76:79]
	v_mfma_f32_16x16x32_bf16 v[68:71], v[162:165], v[214:217], v[68:71]
	s_setprio 0
	s_setprio 1
	v_mfma_f32_16x16x32_bf16 v[120:123], v[166:169], v[182:185], 0
	v_mfma_f32_16x16x32_bf16 v[112:115], v[174:177], v[182:185], 0
	v_mfma_f32_16x16x32_bf16 v[104:107], v[166:169], v[190:193], 0
	v_mfma_f32_16x16x32_bf16 v[96:99], v[174:177], v[190:193], 0
	v_mfma_f32_16x16x32_bf16 v[88:91], v[166:169], v[198:201], 0
	v_mfma_f32_16x16x32_bf16 v[80:83], v[174:177], v[198:201], 0
	v_mfma_f32_16x16x32_bf16 v[72:75], v[166:169], v[210:213], 0
	v_mfma_f32_16x16x32_bf16 v[64:67], v[174:177], v[210:213], 0
	v_mfma_f32_16x16x32_bf16 v[120:123], v[170:173], v[186:189], v[120:123]
	v_mfma_f32_16x16x32_bf16 v[112:115], v[178:181], v[186:189], v[112:115]
	v_mfma_f32_16x16x32_bf16 v[104:107], v[170:173], v[194:197], v[104:107]
	v_mfma_f32_16x16x32_bf16 v[96:99], v[178:181], v[194:197], v[96:99]
	v_mfma_f32_16x16x32_bf16 v[88:91], v[170:173], v[202:205], v[88:91]
	v_mfma_f32_16x16x32_bf16 v[80:83], v[178:181], v[202:205], v[80:83]
	v_mfma_f32_16x16x32_bf16 v[72:75], v[170:173], v[214:217], v[72:75]
	v_mfma_f32_16x16x32_bf16 v[64:67], v[178:181], v[214:217], v[64:67]
	s_setprio 0
	s_barrier
	s_add_i32 s47, s38, s9
	v_lshl_add_u64 v[206:207], s[24:25], 0, v[132:133]
	s_mov_b32 m0, s47
	ds_read_b128 v[182:185], v153 offset:16384
	ds_read_b128 v[186:189], v153 offset:17408
	ds_read_b128 v[190:193], v153 offset:18432
	ds_read_b128 v[194:197], v153 offset:19456
	ds_read_b128 v[198:201], v153 offset:20480
	ds_read_b128 v[202:205], v153 offset:21504
	ds_read_b128 v[210:213], v153 offset:22528
	ds_read_b128 v[214:217], v153 offset:23552
	global_load_lds_dwordx4 v[206:207], off
	s_add_i32 m0, s47, 0x2000
	s_add_u32 s48, s24, 0x40000
	v_lshl_add_u64 v[218:219], s[24:25], 0, v[128:129]
	s_addc_u32 s49, s25, 0
	s_add_i32 s47, s39, s9
	global_load_lds_dwordx4 v[218:219], off
	v_lshl_add_u64 v[220:221], s[48:49], 0, v[132:133]
	s_mov_b32 m0, s47
	v_lshl_add_u64 v[222:223], s[26:27], 0, v[130:131]
	global_load_lds_dwordx4 v[220:221], off
	v_lshl_add_u64 v[220:221], s[48:49], 0, v[128:129]
	s_add_i32 m0, s47, 0x2000
	s_nop 0
	global_load_lds_dwordx4 v[220:221], off
	v_lshl_add_u64 v[220:221], s[26:27], 0, v[134:135]
	s_mov_b32 m0, s21
	s_nop 0
	global_load_lds_dwordx4 v[220:221], off
	s_mov_b32 m0, s30
	s_nop 0
	global_load_lds_dwordx4 v[222:223], off
	s_add_u32 s88, s22, 0xfffbff80
	s_addc_u32 s89, s23, -1
	s_add_u32 s90, s44, 0xffffff00
	s_addc_u32 s91, s45, -1
	s_add_i32 s34, s34, 1
	s_mul_i32 s4, s34, s37
	s_mul_hi_u32 s5, s34, s77
	s_add_i32 s5, s5, s4
	s_mul_i32 s4, s34, s77
	s_add_u32 s16, s4, s82
	s_addc_u32 s17, s5, s28
	v_cmp_gt_i64_e32 vcc, s[16:17], v[142:143]
	v_cmp_lt_i64_e64 s[4:5], s[16:17], v[140:141]
	s_cbranch_vccnz .LBB0_1911
	s_ashr_i32 s12, s16, 31
	s_lshr_b32 s12, s12, 29
	s_add_i32 s12, s16, s12
	s_ashr_i32 s13, s12, 3
	s_and_b32 s12, s12, -8
	s_sub_i32 s12, s16, s12
	s_cmp_lt_i32 s12, 0
	s_cselect_b32 s14, s29, 0xb0
	s_mul_i32 s12, s12, s14
	s_add_i32 s12, s12, s13
	s_mul_hi_i32 s13, s12, 0x2e8ba2e9
	s_lshr_b32 s14, s13, 31
	s_ashr_i32 s13, s13, 5
	s_add_i32 s13, s13, s14
	s_lshl_b32 s14, s13, 3
	s_sub_i32 s15, 64, s14
	s_min_i32 s15, s15, 8
	s_abs_i32 s16, s15
	v_cvt_f32_u32_e32 v228, s16
	s_sub_i32 s18, 0, s16
	s_mulk_i32 s13, 0xb0
	s_sub_i32 s13, s12, s13
	v_rcp_iflag_f32_e32 v228, v228
	s_abs_i32 s12, s13
	s_xor_b32 s17, s13, s15
	s_ashr_i32 s17, s17, 31
	v_mul_f32_e32 v228, 0x4f7ffffe, v228
	v_cvt_u32_f32_e32 v228, v228
	s_nop 0
	v_readfirstlane_b32 s19, v228
	s_mul_i32 s18, s18, s19
	s_mul_hi_u32 s18, s19, s18
	s_add_i32 s19, s19, s18
	s_mul_hi_u32 s18, s12, s19
	s_mul_i32 s19, s18, s16
	s_sub_i32 s12, s12, s19
	s_add_i32 s100, s18, 1
	s_sub_i32 s19, s12, s16
	s_cmp_ge_u32 s12, s16
	s_cselect_b32 s18, s100, s18
	s_cselect_b32 s12, s19, s12
	s_add_i32 s19, s18, 1
	s_cmp_ge_u32 s12, s16
	s_cselect_b32 s12, s19, s18
	s_xor_b32 s12, s12, s17
	s_sub_i32 s12, s12, s17
	s_mul_i32 s15, s12, s15
	s_sub_i32 s13, s13, s15
	s_add_i32 s14, s14, s13
; #define PG8_STAGE(bufoff, gbase, voff) do { _Pragma("unroll") for (int _i = 0; _i < 2; ++_i) \
;         __builtin_amdgcn_global_load_lds((const unsigned*)((const char*)(gbase) + (voff)[_i]), (PG8_LAS unsigned*)(lds + (bufoff) + ldsw + _i * 8192), 16, 0, 0); } while (0)
; #define PG8_LDA(dst, b, h) do { _Pragma("unroll") for (int m = 0; m < 4; ++m) _Pragma("unroll") for (int k = 0; k < 2; ++k) dst[m][k] = *(const PG8_LAS bf16x8*)(lds + PG8_SA(b, h) + aoff + m * 2048 + k * 1024); } while (0)
; #define PG8_LDB(dst, b, h) do { _Pragma("unroll") for (int n = 0; n < 2; ++n) _Pragma("unroll") for (int k = 0; k < 2; ++k) dst[n][k] = *(const PG8_LAS bf16x8*)(lds + PG8_SB(b, h) + boff + n * 2048 + k * 1024); } while (0)
; #define PG8_WAIT_V(n) asm volatile("s_waitcnt vmcnt(" #n ")" ::: "memory")
; #define PG8_WAIT_L(n) asm volatile("s_waitcnt lgkmcnt(" #n ")" ::: "memory")
; #define PG8_BAR __builtin_amdgcn_s_barrier()
; template <class Epi, class Sched, bool ALIGN_EPI = false, bool SP2 = false>
; __device__ __forceinline__ void gemm_phase(PG8_LAS unsigned char* lds, const Gemm g, const Sched& S, const Epi& E, const int wid) {
;     ...
;         const char* nA = has_next ? (const char*)g.A + (size_t)nxt.pm * tstep : cA; const char* nB = has_next ? (const char*)g.Bt + (size_t)nxt.pn * tstep : cB;
;         for (int t = 0; t < nt; t += 2) {
;             const bool last = (t == nt - 2);
;             const char* a1 = cA + (size_t)(t + 1) * kstep;
;             const char* a2 = last ? nA : cA + (size_t)(t + 2) * kstep; const char* b2 = last ? nB : cB + (size_t)(t + 2) * kstep;
;             const char* a3 = a2 + kstep; const char* b3 = b2 + kstep;
;             if (last && has_next) S.a_ready(nxt);
;             if constexpr (SP2) {
;             PG8_LDB(B0, 0, 0); PG8_LDB(B1, 0, 1); PG8_SCHED; PG8_LDA(At, 0, 0); PG8_STAGE(PG8_SA(1, 1), a1 + hstep, voffA);
;             PG8_WAIT_V(8); PG8_WAIT_L(0); PG8_BAR; PG8_MMA(0, 0, At, B0); PG8_MMA(0, 1, At, B1); PG8_BAR; PG8_SCHED;
;             PG8_LDA(At, 0, 1); PG8_STAGE(PG8_SB(0, 0), b2, voffB); PG8_STAGE(PG8_SB(0, 1), b2 + hstep, voffB); PG8_STAGE(PG8_SA(0, 0), a2, voffA);
;             PG8_WAIT_V(8); PG8_WAIT_L(0); PG8_BAR; PG8_MMA(1, 0, At, B0); PG8_MMA(1, 1, At, B1); PG8_BAR; PG8_SCHED;
;             PG8_LDB(B0, 1, 0); PG8_LDB(B1, 1, 1); PG8_SCHED; PG8_LDA(At, 1, 0); PG8_STAGE(PG8_SA(0, 1), a2 + hstep, voffA);
.LBB0_1911:
	s_ashr_i32 s15, s14, 31
	s_lshl_b64 s[16:17], s[14:15], 19
	s_add_u32 s16, s80, s16
	s_addc_u32 s17, s81, s17
	s_and_b64 s[18:19], s[4:5], exec
	s_cselect_b32 s15, s17, s89
	s_cselect_b32 s42, s16, s88
	s_ashr_i32 s13, s12, 31
	s_lshl_b64 s[18:19], s[12:13], 19
	s_add_u32 s18, s10, s18
	s_addc_u32 s19, s11, s19
	s_and_b64 s[100:101], s[4:5], exec
	s_cselect_b32 s13, s19, s91
	s_cselect_b32 s43, s18, s90
	s_waitcnt vmcnt(8)
	s_waitcnt lgkmcnt(0)
	s_barrier
	s_setprio 1
	s_waitcnt lgkmcnt(0)
	v_mfma_f32_16x16x32_bf16 v[60:63], v[144:147], v[182:185], 0
	v_mfma_f32_16x16x32_bf16 v[52:55], v[158:161], v[182:185], 0
	v_mfma_f32_16x16x32_bf16 v[44:47], v[144:147], v[190:193], 0
	v_mfma_f32_16x16x32_bf16 v[36:39], v[158:161], v[190:193], 0
	v_mfma_f32_16x16x32_bf16 v[28:31], v[144:147], v[198:201], 0
	v_mfma_f32_16x16x32_bf16 v[20:23], v[158:161], v[198:201], 0
	v_mfma_f32_16x16x32_bf16 v[12:15], v[144:147], v[210:213], 0
	v_mfma_f32_16x16x32_bf16 v[4:7], v[158:161], v[210:213], 0
	v_mfma_f32_16x16x32_bf16 v[60:63], v[154:157], v[186:189], v[60:63]
	v_mfma_f32_16x16x32_bf16 v[52:55], v[162:165], v[186:189], v[52:55]
	v_mfma_f32_16x16x32_bf16 v[44:47], v[154:157], v[194:197], v[44:47]
	v_mfma_f32_16x16x32_bf16 v[36:39], v[162:165], v[194:197], v[36:39]
	v_mfma_f32_16x16x32_bf16 v[28:31], v[154:157], v[202:205], v[28:31]
	v_mfma_f32_16x16x32_bf16 v[20:23], v[162:165], v[202:205], v[20:23]
	v_mfma_f32_16x16x32_bf16 v[12:15], v[154:157], v[214:217], v[12:15]
	v_mfma_f32_16x16x32_bf16 v[4:7], v[162:165], v[214:217], v[4:7]
	s_setprio 0
	s_setprio 1
	v_mfma_f32_16x16x32_bf16 v[56:59], v[166:169], v[182:185], 0
	v_mfma_f32_16x16x32_bf16 v[48:51], v[174:177], v[182:185], 0
	v_mfma_f32_16x16x32_bf16 v[40:43], v[166:169], v[190:193], 0
	v_mfma_f32_16x16x32_bf16 v[32:35], v[174:177], v[190:193], 0
	v_mfma_f32_16x16x32_bf16 v[24:27], v[166:169], v[198:201], 0
	v_mfma_f32_16x16x32_bf16 v[16:19], v[174:177], v[198:201], 0
	v_mfma_f32_16x16x32_bf16 v[8:11], v[166:169], v[210:213], 0
	v_mfma_f32_16x16x32_bf16 v[0:3], v[174:177], v[210:213], 0
	v_mfma_f32_16x16x32_bf16 v[56:59], v[170:173], v[186:189], v[56:59]
	v_mfma_f32_16x16x32_bf16 v[48:51], v[178:181], v[186:189], v[48:51]
	v_mfma_f32_16x16x32_bf16 v[40:43], v[170:173], v[194:197], v[40:43]
	v_mfma_f32_16x16x32_bf16 v[32:35], v[178:181], v[194:197], v[32:35]
	v_mfma_f32_16x16x32_bf16 v[24:27], v[170:173], v[202:205], v[24:27]
	v_mfma_f32_16x16x32_bf16 v[16:19], v[178:181], v[202:205], v[16:19]
	v_mfma_f32_16x16x32_bf16 v[8:11], v[170:173], v[214:217], v[8:11]
	v_mfma_f32_16x16x32_bf16 v[0:3], v[178:181], v[214:217], v[0:3]
	s_setprio 0
	s_barrier
	s_add_i32 s47, 0, 0x18000
	s_add_i32 s48, 0, 0x1c000
	v_add_u32_e32 v162, s47, v149
	v_add_u32_e32 v178, s48, v149
	ds_read_b128 v[144:147], v162
	ds_read_b128 v[154:157], v162 offset:1024
	ds_read_b128 v[158:161], v162 offset:2048
	ds_read_b128 v[162:165], v162 offset:3072
	ds_read_b128 v[166:169], v178
	ds_read_b128 v[170:173], v178 offset:1024
	ds_read_b128 v[174:177], v178 offset:2048
	ds_read_b128 v[178:181], v178 offset:3072
	s_add_u32 s26, s26, 0x40000
	s_addc_u32 s27, s27, 0
	s_mov_b32 m0, s31
	v_lshl_add_u64 v[224:225], s[26:27], 0, v[134:135]
	ds_read_b128 v[182:185], v153 offset:32768
	ds_read_b128 v[186:189], v153 offset:33792
	ds_read_b128 v[190:193], v153 offset:34816
	ds_read_b128 v[194:197], v153 offset:35840
	ds_read_b128 v[198:201], v153 offset:36864
	ds_read_b128 v[202:205], v153 offset:37888
	ds_read_b128 v[210:213], v153 offset:38912
	ds_read_b128 v[214:217], v153 offset:39936
	global_load_lds_dwordx4 v[224:225], off
	v_lshl_add_u64 v[224:225], s[26:27], 0, v[130:131]
	s_mov_b32 m0, s33
	s_nop 0
	global_load_lds_dwordx4 v[224:225], off
	s_waitcnt vmcnt(8)
	s_waitcnt lgkmcnt(0)
	s_barrier
; #define PG8_STAGE(bufoff, gbase, voff) do { _Pragma("unroll") for (int _i = 0; _i < 2; ++_i) \
;         __builtin_amdgcn_global_load_lds((const unsigned*)((const char*)(gbase) + (voff)[_i]), (PG8_LAS unsigned*)(lds + (bufoff) + ldsw + _i * 8192), 16, 0, 0); } while (0)
; #define PG8_LDA(dst, b, h) do { _Pragma("unroll") for (int m = 0; m < 4; ++m) _Pragma("unroll") for (int k = 0; k < 2; ++k) dst[m][k] = *(const PG8_LAS bf16x8*)(lds + PG8_SA(b, h) + aoff + m * 2048 + k * 1024); } while (0)
; #define PG8_MMA(ai, bj, At, Bt) do { __builtin_amdgcn_s_setprio(1); _Pragma("unroll") for (int m = 0; m < 4; ++m) _Pragma("unroll") for (int n = 0; n < 2; ++n) _Pragma("unroll") for (int k = 0; k < 2; ++k) \
;         acc[ai][bj][m][n] = __builtin_amdgcn_mfma_f32_16x16x32_bf16(Bt[n][k], At[m][k], acc[ai][bj][m][n], 0, 0, 0); __builtin_amdgcn_s_setprio(0); } while (0)
; #define PG8_WAIT_V(n) asm volatile("s_waitcnt vmcnt(" #n ")" ::: "memory")
; #define PG8_WAIT_L(n) asm volatile("s_waitcnt lgkmcnt(" #n ")" ::: "memory")
; #define PG8_BAR __builtin_amdgcn_s_barrier()
; #define PG8_SCHED __builtin_amdgcn_sched_barrier(0)
; template <class Epi, class Sched, bool ALIGN_EPI = false, bool SP2 = false>
; __device__ __forceinline__ void gemm_phase(PG8_LAS unsigned char* lds, const Gemm g, const Sched& S, const Epi& E, const int wid) {
;     ...
;             PG8_WAIT_V(8); PG8_WAIT_L(0); PG8_BAR; PG8_MMA(0, 0, At, B0); PG8_MMA(0, 1, At, B1); PG8_BAR; PG8_SCHED;
;             PG8_LDA(At, 1, 1); PG8_STAGE(PG8_SB(1, 0), b3, voffB); PG8_STAGE(PG8_SB(1, 1), b3 + hstep, voffB); PG8_STAGE(PG8_SA(1, 0), a3, voffA);
;             PG8_WAIT_V(8); PG8_WAIT_L(0); PG8_BAR; PG8_MMA(1, 0, At, B0); PG8_MMA(1, 1, At, B1); PG8_BAR; PG8_SCHED;
	s_setprio 1
	s_waitcnt lgkmcnt(0)
	v_mfma_f32_16x16x32_bf16 v[124:127], v[144:147], v[182:185], v[124:127]
	v_mfma_f32_16x16x32_bf16 v[116:119], v[158:161], v[182:185], v[116:119]
	v_mfma_f32_16x16x32_bf16 v[108:111], v[144:147], v[190:193], v[108:111]
	v_mfma_f32_16x16x32_bf16 v[100:103], v[158:161], v[190:193], v[100:103]
	v_mfma_f32_16x16x32_bf16 v[92:95], v[144:147], v[198:201], v[92:95]
	v_mfma_f32_16x16x32_bf16 v[84:87], v[158:161], v[198:201], v[84:87]
	v_mfma_f32_16x16x32_bf16 v[76:79], v[144:147], v[210:213], v[76:79]
	v_mfma_f32_16x16x32_bf16 v[68:71], v[158:161], v[210:213], v[68:71]
	v_mfma_f32_16x16x32_bf16 v[124:127], v[154:157], v[186:189], v[124:127]
	v_mfma_f32_16x16x32_bf16 v[116:119], v[162:165], v[186:189], v[116:119]
	v_mfma_f32_16x16x32_bf16 v[108:111], v[154:157], v[194:197], v[108:111]
	v_mfma_f32_16x16x32_bf16 v[100:103], v[162:165], v[194:197], v[100:103]
	v_mfma_f32_16x16x32_bf16 v[92:95], v[154:157], v[202:205], v[92:95]
	v_mfma_f32_16x16x32_bf16 v[84:87], v[162:165], v[202:205], v[84:87]
	v_mfma_f32_16x16x32_bf16 v[76:79], v[154:157], v[214:217], v[76:79]
	v_mfma_f32_16x16x32_bf16 v[68:71], v[162:165], v[214:217], v[68:71]
	s_setprio 0
	s_setprio 1
	v_mfma_f32_16x16x32_bf16 v[120:123], v[166:169], v[182:185], v[120:123]
	v_mfma_f32_16x16x32_bf16 v[112:115], v[174:177], v[182:185], v[112:115]
	v_mfma_f32_16x16x32_bf16 v[104:107], v[166:169], v[190:193], v[104:107]
	v_mfma_f32_16x16x32_bf16 v[96:99], v[174:177], v[190:193], v[96:99]
	v_mfma_f32_16x16x32_bf16 v[88:91], v[166:169], v[198:201], v[88:91]
	v_mfma_f32_16x16x32_bf16 v[80:83], v[174:177], v[198:201], v[80:83]
	v_mfma_f32_16x16x32_bf16 v[72:75], v[166:169], v[210:213], v[72:75]
	v_mfma_f32_16x16x32_bf16 v[64:67], v[174:177], v[210:213], v[64:67]
	v_mfma_f32_16x16x32_bf16 v[120:123], v[170:173], v[186:189], v[120:123]
	v_mfma_f32_16x16x32_bf16 v[112:115], v[178:181], v[186:189], v[112:115]
	v_mfma_f32_16x16x32_bf16 v[104:107], v[170:173], v[194:197], v[104:107]
	v_mfma_f32_16x16x32_bf16 v[96:99], v[178:181], v[194:197], v[96:99]
	v_mfma_f32_16x16x32_bf16 v[88:91], v[170:173], v[202:205], v[88:91]
	v_mfma_f32_16x16x32_bf16 v[80:83], v[178:181], v[202:205], v[80:83]
	v_mfma_f32_16x16x32_bf16 v[72:75], v[170:173], v[214:217], v[72:75]
	v_mfma_f32_16x16x32_bf16 v[64:67], v[178:181], v[214:217], v[64:67]
	s_setprio 0
	s_barrier
	s_add_i32 s26, s47, s9
	v_lshl_add_u64 v[206:207], v[206:207], 0, s[2:3]
	s_mov_b32 m0, s26
	ds_read_b128 v[182:185], v153 offset:49152
	ds_read_b128 v[186:189], v153 offset:50176
	ds_read_b128 v[190:193], v153 offset:51200
	ds_read_b128 v[194:197], v153 offset:52224
	ds_read_b128 v[198:201], v153 offset:53248
	ds_read_b128 v[202:205], v153 offset:54272
	ds_read_b128 v[210:213], v153 offset:55296
	ds_read_b128 v[214:217], v153 offset:56320
	global_load_lds_dwordx4 v[206:207], off
	s_add_i32 m0, s26, 0x2000
	s_add_u32 s24, s24, 0x40080
	v_lshl_add_u64 v[206:207], v[218:219], 0, s[2:3]
	s_addc_u32 s25, s25, 0
	s_add_i32 s26, s48, s9
	global_load_lds_dwordx4 v[206:207], off
	v_lshl_add_u64 v[206:207], s[24:25], 0, v[132:133]
	s_mov_b32 m0, s26
	s_nop 0
	global_load_lds_dwordx4 v[206:207], off
	v_lshl_add_u64 v[206:207], s[24:25], 0, v[128:129]
	s_add_i32 m0, s26, 0x2000
	s_nop 0
	global_load_lds_dwordx4 v[206:207], off
	v_lshl_add_u64 v[206:207], v[220:221], 0, s[2:3]
	s_mov_b32 m0, s35
	s_nop 0
	global_load_lds_dwordx4 v[206:207], off
	v_lshl_add_u64 v[206:207], v[222:223], 0, s[2:3]
	s_mov_b32 m0, s36
	s_nop 0
	global_load_lds_dwordx4 v[206:207], off
	s_waitcnt vmcnt(8)
	s_waitcnt lgkmcnt(0)
	s_barrier
	s_setprio 1
	s_waitcnt lgkmcnt(0)
	v_mfma_f32_16x16x32_bf16 v[60:63], v[144:147], v[182:185], v[60:63]
	v_mfma_f32_16x16x32_bf16 v[52:55], v[158:161], v[182:185], v[52:55]
	v_mfma_f32_16x16x32_bf16 v[44:47], v[144:147], v[190:193], v[44:47]
	v_mfma_f32_16x16x32_bf16 v[36:39], v[158:161], v[190:193], v[36:39]
	v_mfma_f32_16x16x32_bf16 v[28:31], v[144:147], v[198:201], v[28:31]
	v_mfma_f32_16x16x32_bf16 v[20:23], v[158:161], v[198:201], v[20:23]
	v_mfma_f32_16x16x32_bf16 v[12:15], v[144:147], v[210:213], v[12:15]
	v_mfma_f32_16x16x32_bf16 v[4:7], v[158:161], v[210:213], v[4:7]
	v_mfma_f32_16x16x32_bf16 v[60:63], v[154:157], v[186:189], v[60:63]
	v_mfma_f32_16x16x32_bf16 v[52:55], v[162:165], v[186:189], v[52:55]
	v_mfma_f32_16x16x32_bf16 v[44:47], v[154:157], v[194:197], v[44:47]
	v_mfma_f32_16x16x32_bf16 v[36:39], v[162:165], v[194:197], v[36:39]
	v_mfma_f32_16x16x32_bf16 v[28:31], v[154:157], v[202:205], v[28:31]
	v_mfma_f32_16x16x32_bf16 v[20:23], v[162:165], v[202:205], v[20:23]
	v_mfma_f32_16x16x32_bf16 v[12:15], v[154:157], v[214:217], v[12:15]
	v_mfma_f32_16x16x32_bf16 v[4:7], v[162:165], v[214:217], v[4:7]
	s_setprio 0
	s_setprio 1
	v_mfma_f32_16x16x32_bf16 v[56:59], v[166:169], v[182:185], v[56:59]
	v_mfma_f32_16x16x32_bf16 v[48:51], v[174:177], v[182:185], v[48:51]
	v_mfma_f32_16x16x32_bf16 v[40:43], v[166:169], v[190:193], v[40:43]
	v_mfma_f32_16x16x32_bf16 v[32:35], v[174:177], v[190:193], v[32:35]
	v_mfma_f32_16x16x32_bf16 v[24:27], v[166:169], v[198:201], v[24:27]
	v_mfma_f32_16x16x32_bf16 v[16:19], v[174:177], v[198:201], v[16:19]
	v_mfma_f32_16x16x32_bf16 v[8:11], v[166:169], v[210:213], v[8:11]
	v_mfma_f32_16x16x32_bf16 v[0:3], v[174:177], v[210:213], v[0:3]
	v_mfma_f32_16x16x32_bf16 v[56:59], v[170:173], v[186:189], v[56:59]
	v_mfma_f32_16x16x32_bf16 v[48:51], v[178:181], v[186:189], v[48:51]
	v_mfma_f32_16x16x32_bf16 v[40:43], v[170:173], v[194:197], v[40:43]
	v_mfma_f32_16x16x32_bf16 v[32:35], v[178:181], v[194:197], v[32:35]
	v_mfma_f32_16x16x32_bf16 v[24:27], v[170:173], v[202:205], v[24:27]
	v_mfma_f32_16x16x32_bf16 v[16:19], v[178:181], v[202:205], v[16:19]
	v_mfma_f32_16x16x32_bf16 v[8:11], v[170:173], v[214:217], v[8:11]
	v_mfma_f32_16x16x32_bf16 v[0:3], v[178:181], v[214:217], v[0:3]
	s_setprio 0
	s_barrier
	s_add_i32 s46, s46, 2
	s_add_u32 s22, s22, 0x100
	s_addc_u32 s23, s23, 0
	s_add_u32 s44, s44, 0x100
	s_addc_u32 s45, s45, 0
	s_cmp_gt_u32 s46, 13
	s_cbranch_scc0 .LBB0_1912
	s_branch .Lkp_exit_4
